# first K-iteration peeled with C=0 MFMAs in five GEMM loops (in-proj, conv-out, attn-o, w_out, ffn-in): no accumulator zeroing
# baseline (speedup 1.0000x reference)
.Lp2_keep:
	s_ashr_i32 s89, s88, 31
	s_lshl_b64 s[12:13], s[88:89], 19
	s_add_u32 s90, s34, s12
	s_addc_u32 s91, s35, s13
	s_and_b64 s[12:13], s[0:1], exec
	s_cselect_b32 s3, s91, s95
	s_cselect_b32 s5, s90, s94
	s_ashr_i32 s87, s86, 31
	s_lshl_b64 s[12:13], s[86:87], 19
	s_add_u32 s92, s14, s12
	s_addc_u32 s93, s15, s13
	s_and_b64 s[12:13], s[0:1], exec
	s_cselect_b32 s8, s93, s97
	s_cselect_b32 s12, s92, s96
	s_add_u32 s94, s94, 0x40080
	s_addc_u32 s95, s95, 0
	s_add_u32 s13, s96, 0x100
	s_addc_u32 s52, s97, 0
	s_mov_b32 s53, -2
	ds_read_b128 v[162:165], v158
	ds_read_b128 v[166:169], v158 offset:1024
	ds_read_b128 v[170:173], v158 offset:2048
	ds_read_b128 v[174:177], v158 offset:3072
	ds_read_b128 v[178:181], v159
	ds_read_b128 v[182:185], v159 offset:1024
	ds_read_b128 v[186:189], v159 offset:2048
	ds_read_b128 v[190:193], v159 offset:3072
	s_add_u32 s65, s94, 0xfffc0080
	s_addc_u32 s66, s95, -1
	s_cmp_eq_u32 s53, 12
	s_cselect_b32 vcc_hi, s3, s66
	s_cselect_b32 vcc_lo, s5, s65
	s_cselect_b32 s97, s8, s52
	s_cselect_b32 s96, s12, s13
	v_lshl_add_u64 v[148:149], s[94:95], 0, v[140:141]
	s_add_i32 m0, s7, 0xc000
	ds_read_b128 v[198:201], v160
	ds_read_b128 v[202:205], v160 offset:1024
	ds_read_b128 v[206:209], v160 offset:2048
	ds_read_b128 v[210:213], v160 offset:3072
	ds_read_b128 v[214:217], v160 offset:4096
	ds_read_b128 v[218:221], v160 offset:5120
	ds_read_b128 v[222:225], v160 offset:6144
	ds_read_b128 v[226:229], v160 offset:7168
	global_load_lds_dwordx4 v[148:149], off
	v_lshl_add_u64 v[148:149], s[94:95], 0, v[142:143]
	s_add_i32 m0, s7, 0xe000
	s_nop 0
	global_load_lds_dwordx4 v[148:149], off
	s_waitcnt vmcnt(8)
	s_waitcnt lgkmcnt(0)
	s_barrier
	s_setprio 1
	s_waitcnt lgkmcnt(0)
	v_mfma_f32_16x16x32_bf16 v[124:127], v[162:165], v[198:201], 0
	v_mfma_f32_16x16x32_bf16 v[120:123], v[170:173], v[198:201], 0
	v_mfma_f32_16x16x32_bf16 v[108:111], v[162:165], v[206:209], 0
	v_mfma_f32_16x16x32_bf16 v[104:107], v[170:173], v[206:209], 0
	v_mfma_f32_16x16x32_bf16 v[92:95], v[162:165], v[214:217], 0
	v_mfma_f32_16x16x32_bf16 v[88:91], v[170:173], v[214:217], 0
	v_mfma_f32_16x16x32_bf16 v[76:79], v[162:165], v[222:225], 0
	v_mfma_f32_16x16x32_bf16 v[72:75], v[170:173], v[222:225], 0
	v_mfma_f32_16x16x32_bf16 v[124:127], v[166:169], v[202:205], v[124:127]
	v_mfma_f32_16x16x32_bf16 v[120:123], v[174:177], v[202:205], v[120:123]
	v_mfma_f32_16x16x32_bf16 v[108:111], v[166:169], v[210:213], v[108:111]
	v_mfma_f32_16x16x32_bf16 v[104:107], v[174:177], v[210:213], v[104:107]
	v_mfma_f32_16x16x32_bf16 v[92:95], v[166:169], v[218:221], v[92:95]
	v_mfma_f32_16x16x32_bf16 v[88:91], v[174:177], v[218:221], v[88:91]
	v_mfma_f32_16x16x32_bf16 v[76:79], v[166:169], v[226:229], v[76:79]
	v_mfma_f32_16x16x32_bf16 v[72:75], v[174:177], v[226:229], v[72:75]
	s_setprio 0
	s_setprio 1
	v_mfma_f32_16x16x32_bf16 v[116:119], v[178:181], v[198:201], 0
	v_mfma_f32_16x16x32_bf16 v[112:115], v[186:189], v[198:201], 0
	v_mfma_f32_16x16x32_bf16 v[100:103], v[178:181], v[206:209], 0
	v_mfma_f32_16x16x32_bf16 v[96:99], v[186:189], v[206:209], 0
	v_mfma_f32_16x16x32_bf16 v[84:87], v[178:181], v[214:217], 0
	v_mfma_f32_16x16x32_bf16 v[80:83], v[186:189], v[214:217], 0
	v_mfma_f32_16x16x32_bf16 v[68:71], v[178:181], v[222:225], 0
	v_mfma_f32_16x16x32_bf16 v[64:67], v[186:189], v[222:225], 0
	v_mfma_f32_16x16x32_bf16 v[116:119], v[182:185], v[202:205], v[116:119]
	v_mfma_f32_16x16x32_bf16 v[112:115], v[190:193], v[202:205], v[112:115]
	v_mfma_f32_16x16x32_bf16 v[100:103], v[182:185], v[210:213], v[100:103]
	v_mfma_f32_16x16x32_bf16 v[96:99], v[190:193], v[210:213], v[96:99]
	v_mfma_f32_16x16x32_bf16 v[84:87], v[182:185], v[218:221], v[84:87]
	v_mfma_f32_16x16x32_bf16 v[80:83], v[190:193], v[218:221], v[80:83]
	v_mfma_f32_16x16x32_bf16 v[68:71], v[182:185], v[226:229], v[68:71]
	v_mfma_f32_16x16x32_bf16 v[64:67], v[190:193], v[226:229], v[64:67]
	s_setprio 0
	s_barrier
	s_add_i32 s65, s58, s75
	v_lshl_add_u64 v[148:149], s[96:97], 0, v[130:131]
	s_mov_b32 m0, s65
	ds_read_b128 v[198:201], v160 offset:16384
	ds_read_b128 v[202:205], v160 offset:17408
	ds_read_b128 v[206:209], v160 offset:18432
	ds_read_b128 v[210:213], v160 offset:19456
	ds_read_b128 v[214:217], v160 offset:20480
	ds_read_b128 v[218:221], v160 offset:21504
	ds_read_b128 v[222:225], v160 offset:22528
	ds_read_b128 v[226:229], v160 offset:23552
	global_load_lds_dwordx4 v[148:149], off
	s_add_i32 m0, s65, 0x2000
	s_add_u32 s66, s96, 0x40000
	v_lshl_add_u64 v[194:195], s[96:97], 0, v[134:135]
	s_addc_u32 s67, s97, 0
	s_add_i32 s65, s59, s75
	global_load_lds_dwordx4 v[194:195], off
	v_lshl_add_u64 v[230:231], s[66:67], 0, v[130:131]
	s_mov_b32 m0, s65
	v_lshl_add_u64 v[232:233], vcc, 0, v[132:133]
	global_load_lds_dwordx4 v[230:231], off
	v_lshl_add_u64 v[230:231], s[66:67], 0, v[134:135]
	s_add_i32 m0, s65, 0x2000
	s_nop 0
	global_load_lds_dwordx4 v[230:231], off
	v_lshl_add_u64 v[230:231], vcc, 0, v[128:129]
	s_mov_b32 m0, s7
	s_nop 0
	global_load_lds_dwordx4 v[230:231], off
	s_mov_b32 m0, s77
	s_nop 0
	global_load_lds_dwordx4 v[232:233], off
	s_waitcnt vmcnt(8)
	s_waitcnt lgkmcnt(0)
	s_barrier
	s_setprio 1
	s_waitcnt lgkmcnt(0)
	v_mfma_f32_16x16x32_bf16 v[60:63], v[162:165], v[198:201], 0
	v_mfma_f32_16x16x32_bf16 v[56:59], v[170:173], v[198:201], 0
	v_mfma_f32_16x16x32_bf16 v[44:47], v[162:165], v[206:209], 0
	v_mfma_f32_16x16x32_bf16 v[40:43], v[170:173], v[206:209], 0
	v_mfma_f32_16x16x32_bf16 v[28:31], v[162:165], v[214:217], 0
	v_mfma_f32_16x16x32_bf16 v[24:27], v[170:173], v[214:217], 0
	v_mfma_f32_16x16x32_bf16 v[12:15], v[162:165], v[222:225], 0
	v_mfma_f32_16x16x32_bf16 v[8:11], v[170:173], v[222:225], 0
	v_mfma_f32_16x16x32_bf16 v[60:63], v[166:169], v[202:205], v[60:63]
	v_mfma_f32_16x16x32_bf16 v[56:59], v[174:177], v[202:205], v[56:59]
	v_mfma_f32_16x16x32_bf16 v[44:47], v[166:169], v[210:213], v[44:47]
	v_mfma_f32_16x16x32_bf16 v[40:43], v[174:177], v[210:213], v[40:43]
	v_mfma_f32_16x16x32_bf16 v[28:31], v[166:169], v[218:221], v[28:31]
	v_mfma_f32_16x16x32_bf16 v[24:27], v[174:177], v[218:221], v[24:27]
	v_mfma_f32_16x16x32_bf16 v[12:15], v[166:169], v[226:229], v[12:15]
	v_mfma_f32_16x16x32_bf16 v[8:11], v[174:177], v[226:229], v[8:11]
	s_setprio 0
	s_setprio 1
	v_mfma_f32_16x16x32_bf16 v[52:55], v[178:181], v[198:201], 0
	v_mfma_f32_16x16x32_bf16 v[48:51], v[186:189], v[198:201], 0
	v_mfma_f32_16x16x32_bf16 v[36:39], v[178:181], v[206:209], 0
	v_mfma_f32_16x16x32_bf16 v[32:35], v[186:189], v[206:209], 0
	v_mfma_f32_16x16x32_bf16 v[20:23], v[178:181], v[214:217], 0
	v_mfma_f32_16x16x32_bf16 v[16:19], v[186:189], v[214:217], 0
	v_mfma_f32_16x16x32_bf16 v[4:7], v[178:181], v[222:225], 0
	v_mfma_f32_16x16x32_bf16 v[0:3], v[186:189], v[222:225], 0
	v_mfma_f32_16x16x32_bf16 v[52:55], v[182:185], v[202:205], v[52:55]
	v_mfma_f32_16x16x32_bf16 v[48:51], v[190:193], v[202:205], v[48:51]
	v_mfma_f32_16x16x32_bf16 v[36:39], v[182:185], v[210:213], v[36:39]
	v_mfma_f32_16x16x32_bf16 v[32:35], v[190:193], v[210:213], v[32:35]
	v_mfma_f32_16x16x32_bf16 v[20:23], v[182:185], v[218:221], v[20:23]
	v_mfma_f32_16x16x32_bf16 v[16:19], v[190:193], v[218:221], v[16:19]
	v_mfma_f32_16x16x32_bf16 v[4:7], v[182:185], v[226:229], v[4:7]
	v_mfma_f32_16x16x32_bf16 v[0:3], v[190:193], v[226:229], v[0:3]
	s_setprio 0
	s_barrier
	s_add_i32 s65, 0, 0x18000
	v_add_u32_e32 v136, s65, v150
	s_add_i32 s70, 0, 0x1c000
	ds_read_b128 v[162:165], v136
	ds_read_b128 v[166:169], v136 offset:1024
	ds_read_b128 v[170:173], v136 offset:2048
	ds_read_b128 v[174:177], v136 offset:3072
	v_add_u32_e32 v136, s70, v150
	ds_read_b128 v[178:181], v136
	ds_read_b128 v[182:185], v136 offset:1024
	ds_read_b128 v[186:189], v136 offset:2048
	ds_read_b128 v[190:193], v136 offset:3072
	s_add_u32 s66, vcc_lo, 0x40000
	s_addc_u32 s67, vcc_hi, 0
	s_mov_b32 m0, s78
	v_lshl_add_u64 v[234:235], s[66:67], 0, v[128:129]
	ds_read_b128 v[198:201], v160 offset:32768
	ds_read_b128 v[202:205], v160 offset:33792
	ds_read_b128 v[206:209], v160 offset:34816
	ds_read_b128 v[210:213], v160 offset:35840
	ds_read_b128 v[214:217], v160 offset:36864
	ds_read_b128 v[218:221], v160 offset:37888
	ds_read_b128 v[222:225], v160 offset:38912
	ds_read_b128 v[226:229], v160 offset:39936
	global_load_lds_dwordx4 v[234:235], off
	v_lshl_add_u64 v[234:235], s[66:67], 0, v[132:133]
	s_mov_b32 m0, s79
	s_nop 0
	global_load_lds_dwordx4 v[234:235], off
	s_waitcnt vmcnt(8)
	s_waitcnt lgkmcnt(0)
	s_barrier
	s_setprio 1
	s_waitcnt lgkmcnt(0)
	v_mfma_f32_16x16x32_bf16 v[124:127], v[162:165], v[198:201], v[124:127]
	v_mfma_f32_16x16x32_bf16 v[120:123], v[170:173], v[198:201], v[120:123]
	v_mfma_f32_16x16x32_bf16 v[108:111], v[162:165], v[206:209], v[108:111]
	v_mfma_f32_16x16x32_bf16 v[104:107], v[170:173], v[206:209], v[104:107]
	v_mfma_f32_16x16x32_bf16 v[92:95], v[162:165], v[214:217], v[92:95]
	v_mfma_f32_16x16x32_bf16 v[88:91], v[170:173], v[214:217], v[88:91]
	v_mfma_f32_16x16x32_bf16 v[76:79], v[162:165], v[222:225], v[76:79]
	v_mfma_f32_16x16x32_bf16 v[72:75], v[170:173], v[222:225], v[72:75]
	v_mfma_f32_16x16x32_bf16 v[124:127], v[166:169], v[202:205], v[124:127]
	v_mfma_f32_16x16x32_bf16 v[120:123], v[174:177], v[202:205], v[120:123]
	v_mfma_f32_16x16x32_bf16 v[108:111], v[166:169], v[210:213], v[108:111]
	v_mfma_f32_16x16x32_bf16 v[104:107], v[174:177], v[210:213], v[104:107]
	v_mfma_f32_16x16x32_bf16 v[92:95], v[166:169], v[218:221], v[92:95]
	v_mfma_f32_16x16x32_bf16 v[88:91], v[174:177], v[218:221], v[88:91]
	v_mfma_f32_16x16x32_bf16 v[76:79], v[166:169], v[226:229], v[76:79]
	v_mfma_f32_16x16x32_bf16 v[72:75], v[174:177], v[226:229], v[72:75]
	s_setprio 0
	s_setprio 1
	v_mfma_f32_16x16x32_bf16 v[116:119], v[178:181], v[198:201], v[116:119]
	v_mfma_f32_16x16x32_bf16 v[112:115], v[186:189], v[198:201], v[112:115]
	v_mfma_f32_16x16x32_bf16 v[100:103], v[178:181], v[206:209], v[100:103]
	v_mfma_f32_16x16x32_bf16 v[96:99], v[186:189], v[206:209], v[96:99]
	v_mfma_f32_16x16x32_bf16 v[84:87], v[178:181], v[214:217], v[84:87]
	v_mfma_f32_16x16x32_bf16 v[80:83], v[186:189], v[214:217], v[80:83]
	v_mfma_f32_16x16x32_bf16 v[68:71], v[178:181], v[222:225], v[68:71]
	v_mfma_f32_16x16x32_bf16 v[64:67], v[186:189], v[222:225], v[64:67]
	v_mfma_f32_16x16x32_bf16 v[116:119], v[182:185], v[202:205], v[116:119]
	v_mfma_f32_16x16x32_bf16 v[112:115], v[190:193], v[202:205], v[112:115]
	v_mfma_f32_16x16x32_bf16 v[100:103], v[182:185], v[210:213], v[100:103]
	v_mfma_f32_16x16x32_bf16 v[96:99], v[190:193], v[210:213], v[96:99]
	v_mfma_f32_16x16x32_bf16 v[84:87], v[182:185], v[218:221], v[84:87]
	v_mfma_f32_16x16x32_bf16 v[80:83], v[190:193], v[218:221], v[80:83]
	v_mfma_f32_16x16x32_bf16 v[68:71], v[182:185], v[226:229], v[68:71]
	v_mfma_f32_16x16x32_bf16 v[64:67], v[190:193], v[226:229], v[64:67]
	s_setprio 0
	s_barrier
	s_add_i32 s65, s65, s75
	v_lshl_add_u64 v[148:149], v[148:149], 0, s[82:83]
	s_mov_b32 m0, s65
	ds_read_b128 v[198:201], v160 offset:49152
	ds_read_b128 v[202:205], v160 offset:50176
	ds_read_b128 v[206:209], v160 offset:51200
	ds_read_b128 v[210:213], v160 offset:52224
	ds_read_b128 v[214:217], v160 offset:53248
	ds_read_b128 v[218:221], v160 offset:54272
	ds_read_b128 v[222:225], v160 offset:55296
	ds_read_b128 v[226:229], v160 offset:56320
	global_load_lds_dwordx4 v[148:149], off
	s_add_i32 m0, s65, 0x2000
	s_add_u32 s66, s96, 0x40080
	v_lshl_add_u64 v[148:149], v[194:195], 0, s[82:83]
	s_addc_u32 s67, s97, 0
	s_add_i32 s65, s70, s75
	global_load_lds_dwordx4 v[148:149], off
	v_lshl_add_u64 v[148:149], s[66:67], 0, v[130:131]
	s_mov_b32 m0, s65
	s_nop 0
	global_load_lds_dwordx4 v[148:149], off
	v_lshl_add_u64 v[148:149], s[66:67], 0, v[134:135]
	s_add_i32 m0, s65, 0x2000
	s_nop 0
	global_load_lds_dwordx4 v[148:149], off
	v_lshl_add_u64 v[148:149], v[230:231], 0, s[82:83]
	s_mov_b32 m0, s55
	s_nop 0
	global_load_lds_dwordx4 v[148:149], off
	v_lshl_add_u64 v[148:149], v[232:233], 0, s[82:83]
	s_mov_b32 m0, s56
	s_nop 0
	global_load_lds_dwordx4 v[148:149], off
	s_waitcnt vmcnt(8)
	s_waitcnt lgkmcnt(0)
	s_barrier
	s_setprio 1
	s_waitcnt lgkmcnt(0)
	v_mfma_f32_16x16x32_bf16 v[60:63], v[162:165], v[198:201], v[60:63]
	v_mfma_f32_16x16x32_bf16 v[56:59], v[170:173], v[198:201], v[56:59]
	v_mfma_f32_16x16x32_bf16 v[44:47], v[162:165], v[206:209], v[44:47]
	v_mfma_f32_16x16x32_bf16 v[40:43], v[170:173], v[206:209], v[40:43]
	v_mfma_f32_16x16x32_bf16 v[28:31], v[162:165], v[214:217], v[28:31]
	v_mfma_f32_16x16x32_bf16 v[24:27], v[170:173], v[214:217], v[24:27]
	v_mfma_f32_16x16x32_bf16 v[12:15], v[162:165], v[222:225], v[12:15]
	v_mfma_f32_16x16x32_bf16 v[8:11], v[170:173], v[222:225], v[8:11]
	v_mfma_f32_16x16x32_bf16 v[60:63], v[166:169], v[202:205], v[60:63]
	v_mfma_f32_16x16x32_bf16 v[56:59], v[174:177], v[202:205], v[56:59]
	v_mfma_f32_16x16x32_bf16 v[44:47], v[166:169], v[210:213], v[44:47]
	v_mfma_f32_16x16x32_bf16 v[40:43], v[174:177], v[210:213], v[40:43]
	v_mfma_f32_16x16x32_bf16 v[28:31], v[166:169], v[218:221], v[28:31]
	v_mfma_f32_16x16x32_bf16 v[24:27], v[174:177], v[218:221], v[24:27]
	v_mfma_f32_16x16x32_bf16 v[12:15], v[166:169], v[226:229], v[12:15]
	v_mfma_f32_16x16x32_bf16 v[8:11], v[174:177], v[226:229], v[8:11]
	s_setprio 0
	s_setprio 1
	v_mfma_f32_16x16x32_bf16 v[52:55], v[178:181], v[198:201], v[52:55]
	v_mfma_f32_16x16x32_bf16 v[48:51], v[186:189], v[198:201], v[48:51]
	v_mfma_f32_16x16x32_bf16 v[36:39], v[178:181], v[206:209], v[36:39]
	v_mfma_f32_16x16x32_bf16 v[32:35], v[186:189], v[206:209], v[32:35]
	v_mfma_f32_16x16x32_bf16 v[20:23], v[178:181], v[214:217], v[20:23]
	v_mfma_f32_16x16x32_bf16 v[16:19], v[186:189], v[214:217], v[16:19]
	v_mfma_f32_16x16x32_bf16 v[4:7], v[178:181], v[222:225], v[4:7]
	v_mfma_f32_16x16x32_bf16 v[0:3], v[186:189], v[222:225], v[0:3]
	v_mfma_f32_16x16x32_bf16 v[52:55], v[182:185], v[202:205], v[52:55]
	v_mfma_f32_16x16x32_bf16 v[48:51], v[190:193], v[202:205], v[48:51]
	v_mfma_f32_16x16x32_bf16 v[36:39], v[182:185], v[210:213], v[36:39]
	v_mfma_f32_16x16x32_bf16 v[32:35], v[190:193], v[210:213], v[32:35]
	v_mfma_f32_16x16x32_bf16 v[20:23], v[182:185], v[218:221], v[20:23]
	v_mfma_f32_16x16x32_bf16 v[16:19], v[190:193], v[218:221], v[16:19]
	v_mfma_f32_16x16x32_bf16 v[4:7], v[182:185], v[226:229], v[4:7]
	v_mfma_f32_16x16x32_bf16 v[0:3], v[190:193], v[226:229], v[0:3]
	s_setprio 0
	s_barrier
	s_add_i32 s53, s53, 2
	s_add_u32 s94, s94, 0x100
	s_addc_u32 s95, s95, 0
	s_add_u32 s13, s13, 0x100
	s_addc_u32 s52, s52, 0

.LBB0_591:
	s_ashr_i32 s83, s82, 31
	s_lshl_b64 s[8:9], s[82:83], 19
	s_add_u32 s84, s34, s8
	s_addc_u32 s85, s35, s9
	s_and_b64 s[8:9], s[0:1], exec
	s_cselect_b32 s8, s85, s91
	s_cselect_b32 s9, s84, s90
	s_ashr_i32 s67, s66, 31
	s_lshl_b64 s[70:71], s[66:67], 19
	v_readlane_b32 s36, v250, 40
	v_readlane_b32 s37, v250, 41
	s_add_u32 s86, s36, s70
	s_addc_u32 s87, s37, s71
	s_and_b64 s[70:71], s[0:1], exec
	s_cselect_b32 s67, s87, s93
	s_cselect_b32 s70, s86, s92
	s_add_u32 s90, s90, 0x40080
	s_addc_u32 s91, s91, 0
	s_add_u32 s71, s92, 0x100
	s_addc_u32 s72, s93, 0
	s_mov_b32 s73, -2
	ds_read_b128 v[146:149], v151
	ds_read_b128 v[154:157], v151 offset:1024
	ds_read_b128 v[158:161], v151 offset:2048
	ds_read_b128 v[162:165], v151 offset:3072
	ds_read_b128 v[166:169], v152
	ds_read_b128 v[170:173], v152 offset:1024
	ds_read_b128 v[174:177], v152 offset:2048
	ds_read_b128 v[178:181], v152 offset:3072
	s_add_u32 s48, s90, 0xfffc0080
	s_addc_u32 s49, s91, -1
	s_cmp_eq_u32 s73, 12
	s_cselect_b32 s95, s8, s49
	s_cselect_b32 s94, s9, s48
	s_cselect_b32 s93, s67, s72
	s_cselect_b32 s92, s70, s71
	v_lshl_add_u64 v[194:195], s[90:91], 0, v[138:139]
	s_add_i32 m0, s46, 0xc000
	ds_read_b128 v[182:185], v153
	ds_read_b128 v[186:189], v153 offset:1024
	ds_read_b128 v[190:193], v153 offset:2048
	ds_read_b128 v[202:205], v153 offset:3072
	ds_read_b128 v[206:209], v153 offset:4096
	ds_read_b128 v[210:213], v153 offset:5120
	ds_read_b128 v[214:217], v153 offset:6144
	ds_read_b128 v[218:221], v153 offset:7168
	global_load_lds_dwordx4 v[194:195], off
	v_lshl_add_u64 v[194:195], s[90:91], 0, v[140:141]
	s_add_i32 m0, s46, 0xe000
	s_nop 0
	global_load_lds_dwordx4 v[194:195], off
	s_waitcnt vmcnt(8)
	s_waitcnt lgkmcnt(0)
	s_barrier
	s_setprio 1
	s_waitcnt lgkmcnt(0)
	v_mfma_f32_16x16x32_bf16 v[124:127], v[146:149], v[182:185], 0
	v_mfma_f32_16x16x32_bf16 v[120:123], v[158:161], v[182:185], 0
	v_mfma_f32_16x16x32_bf16 v[108:111], v[146:149], v[190:193], 0
	v_mfma_f32_16x16x32_bf16 v[104:107], v[158:161], v[190:193], 0
	v_mfma_f32_16x16x32_bf16 v[92:95], v[146:149], v[206:209], 0
	v_mfma_f32_16x16x32_bf16 v[88:91], v[158:161], v[206:209], 0
	v_mfma_f32_16x16x32_bf16 v[76:79], v[146:149], v[214:217], 0
	v_mfma_f32_16x16x32_bf16 v[72:75], v[158:161], v[214:217], 0
	v_mfma_f32_16x16x32_bf16 v[124:127], v[154:157], v[186:189], v[124:127]
	v_mfma_f32_16x16x32_bf16 v[120:123], v[162:165], v[186:189], v[120:123]
	v_mfma_f32_16x16x32_bf16 v[108:111], v[154:157], v[202:205], v[108:111]
	v_mfma_f32_16x16x32_bf16 v[104:107], v[162:165], v[202:205], v[104:107]
	v_mfma_f32_16x16x32_bf16 v[92:95], v[154:157], v[210:213], v[92:95]
	v_mfma_f32_16x16x32_bf16 v[88:91], v[162:165], v[210:213], v[88:91]
	v_mfma_f32_16x16x32_bf16 v[76:79], v[154:157], v[218:221], v[76:79]
	v_mfma_f32_16x16x32_bf16 v[72:75], v[162:165], v[218:221], v[72:75]
	s_setprio 0
	s_setprio 1
	v_mfma_f32_16x16x32_bf16 v[116:119], v[166:169], v[182:185], 0
	v_mfma_f32_16x16x32_bf16 v[112:115], v[174:177], v[182:185], 0
	v_mfma_f32_16x16x32_bf16 v[100:103], v[166:169], v[190:193], 0
	v_mfma_f32_16x16x32_bf16 v[96:99], v[174:177], v[190:193], 0
	v_mfma_f32_16x16x32_bf16 v[84:87], v[166:169], v[206:209], 0
	v_mfma_f32_16x16x32_bf16 v[80:83], v[174:177], v[206:209], 0
	v_mfma_f32_16x16x32_bf16 v[68:71], v[166:169], v[214:217], 0
	v_mfma_f32_16x16x32_bf16 v[64:67], v[174:177], v[214:217], 0
	v_mfma_f32_16x16x32_bf16 v[116:119], v[170:173], v[186:189], v[116:119]
	v_mfma_f32_16x16x32_bf16 v[112:115], v[178:181], v[186:189], v[112:115]
	v_mfma_f32_16x16x32_bf16 v[100:103], v[170:173], v[202:205], v[100:103]
	v_mfma_f32_16x16x32_bf16 v[96:99], v[178:181], v[202:205], v[96:99]
	v_mfma_f32_16x16x32_bf16 v[84:87], v[170:173], v[210:213], v[84:87]
	v_mfma_f32_16x16x32_bf16 v[80:83], v[178:181], v[210:213], v[80:83]
	v_mfma_f32_16x16x32_bf16 v[68:71], v[170:173], v[218:221], v[68:71]
	v_mfma_f32_16x16x32_bf16 v[64:67], v[178:181], v[218:221], v[64:67]
	s_setprio 0
	s_barrier
	s_add_i32 s48, s61, s15
	v_lshl_add_u64 v[194:195], s[92:93], 0, v[132:133]
	s_mov_b32 m0, s48
	ds_read_b128 v[182:185], v153 offset:16384
	ds_read_b128 v[186:189], v153 offset:17408
	ds_read_b128 v[190:193], v153 offset:18432
	ds_read_b128 v[202:205], v153 offset:19456
	ds_read_b128 v[206:209], v153 offset:20480
	ds_read_b128 v[210:213], v153 offset:21504
	ds_read_b128 v[214:217], v153 offset:22528
	ds_read_b128 v[218:221], v153 offset:23552
	global_load_lds_dwordx4 v[194:195], off
	s_add_i32 m0, s48, 0x2000
	s_add_u32 s78, s92, 0x40000
	v_lshl_add_u64 v[222:223], s[92:93], 0, v[128:129]
	s_addc_u32 s79, s93, 0
	s_add_i32 s48, s64, s15
	global_load_lds_dwordx4 v[222:223], off
	v_lshl_add_u64 v[224:225], s[78:79], 0, v[132:133]
	s_mov_b32 m0, s48
	v_lshl_add_u64 v[226:227], s[94:95], 0, v[130:131]
	global_load_lds_dwordx4 v[224:225], off
	v_lshl_add_u64 v[224:225], s[78:79], 0, v[128:129]
	s_add_i32 m0, s48, 0x2000
	s_nop 0
	global_load_lds_dwordx4 v[224:225], off
	v_lshl_add_u64 v[224:225], s[94:95], 0, v[134:135]
	s_mov_b32 m0, s46
	s_nop 0
	global_load_lds_dwordx4 v[224:225], off
	s_mov_b32 m0, s47
	s_nop 0
	global_load_lds_dwordx4 v[226:227], off
	s_waitcnt vmcnt(8)
	s_waitcnt lgkmcnt(0)
	s_barrier
	s_setprio 1
	s_waitcnt lgkmcnt(0)
	v_mfma_f32_16x16x32_bf16 v[60:63], v[146:149], v[182:185], 0
	v_mfma_f32_16x16x32_bf16 v[56:59], v[158:161], v[182:185], 0
	v_mfma_f32_16x16x32_bf16 v[44:47], v[146:149], v[190:193], 0
	v_mfma_f32_16x16x32_bf16 v[40:43], v[158:161], v[190:193], 0
	v_mfma_f32_16x16x32_bf16 v[28:31], v[146:149], v[206:209], 0
	v_mfma_f32_16x16x32_bf16 v[24:27], v[158:161], v[206:209], 0
	v_mfma_f32_16x16x32_bf16 v[12:15], v[146:149], v[214:217], 0
	v_mfma_f32_16x16x32_bf16 v[8:11], v[158:161], v[214:217], 0
	v_mfma_f32_16x16x32_bf16 v[60:63], v[154:157], v[186:189], v[60:63]
	v_mfma_f32_16x16x32_bf16 v[56:59], v[162:165], v[186:189], v[56:59]
	v_mfma_f32_16x16x32_bf16 v[44:47], v[154:157], v[202:205], v[44:47]
	v_mfma_f32_16x16x32_bf16 v[40:43], v[162:165], v[202:205], v[40:43]
	v_mfma_f32_16x16x32_bf16 v[28:31], v[154:157], v[210:213], v[28:31]
	v_mfma_f32_16x16x32_bf16 v[24:27], v[162:165], v[210:213], v[24:27]
	v_mfma_f32_16x16x32_bf16 v[12:15], v[154:157], v[218:221], v[12:15]
	v_mfma_f32_16x16x32_bf16 v[8:11], v[162:165], v[218:221], v[8:11]
	s_setprio 0
	s_setprio 1
	v_mfma_f32_16x16x32_bf16 v[52:55], v[166:169], v[182:185], 0
	v_mfma_f32_16x16x32_bf16 v[48:51], v[174:177], v[182:185], 0
	v_mfma_f32_16x16x32_bf16 v[36:39], v[166:169], v[190:193], 0
	v_mfma_f32_16x16x32_bf16 v[32:35], v[174:177], v[190:193], 0
	v_mfma_f32_16x16x32_bf16 v[20:23], v[166:169], v[206:209], 0
	v_mfma_f32_16x16x32_bf16 v[16:19], v[174:177], v[206:209], 0
	v_mfma_f32_16x16x32_bf16 v[4:7], v[166:169], v[214:217], 0
	v_mfma_f32_16x16x32_bf16 v[0:3], v[174:177], v[214:217], 0
	v_mfma_f32_16x16x32_bf16 v[52:55], v[170:173], v[186:189], v[52:55]
	v_mfma_f32_16x16x32_bf16 v[48:51], v[178:181], v[186:189], v[48:51]
	v_mfma_f32_16x16x32_bf16 v[36:39], v[170:173], v[202:205], v[36:39]
	v_mfma_f32_16x16x32_bf16 v[32:35], v[178:181], v[202:205], v[32:35]
	v_mfma_f32_16x16x32_bf16 v[20:23], v[170:173], v[210:213], v[20:23]
	v_mfma_f32_16x16x32_bf16 v[16:19], v[178:181], v[210:213], v[16:19]
	v_mfma_f32_16x16x32_bf16 v[4:7], v[170:173], v[218:221], v[4:7]
	v_mfma_f32_16x16x32_bf16 v[0:3], v[178:181], v[218:221], v[0:3]
	s_setprio 0
	s_barrier
	s_add_i32 s48, 0, 0x18000
	s_add_i32 s49, 0, 0x1c000
	v_add_u32_e32 v162, s48, v150
	v_add_u32_e32 v178, s49, v150
	ds_read_b128 v[146:149], v162
	ds_read_b128 v[154:157], v162 offset:1024
	ds_read_b128 v[158:161], v162 offset:2048
	ds_read_b128 v[162:165], v162 offset:3072
	ds_read_b128 v[166:169], v178
	ds_read_b128 v[170:173], v178 offset:1024
	ds_read_b128 v[174:177], v178 offset:2048
	ds_read_b128 v[178:181], v178 offset:3072
	s_add_u32 s78, s94, 0x40000
	s_addc_u32 s79, s95, 0
	s_mov_b32 m0, s52
	v_lshl_add_u64 v[228:229], s[78:79], 0, v[134:135]
	ds_read_b128 v[182:185], v153 offset:32768
	ds_read_b128 v[186:189], v153 offset:33792
	ds_read_b128 v[190:193], v153 offset:34816
	ds_read_b128 v[202:205], v153 offset:35840
	ds_read_b128 v[206:209], v153 offset:36864
	ds_read_b128 v[210:213], v153 offset:37888
	ds_read_b128 v[214:217], v153 offset:38912
	ds_read_b128 v[218:221], v153 offset:39936
	global_load_lds_dwordx4 v[228:229], off
	v_lshl_add_u64 v[228:229], s[78:79], 0, v[130:131]
	s_mov_b32 m0, s53
	s_nop 0
	global_load_lds_dwordx4 v[228:229], off
	s_waitcnt vmcnt(8)
	s_waitcnt lgkmcnt(0)
	s_barrier
	s_setprio 1
	s_waitcnt lgkmcnt(0)
	v_mfma_f32_16x16x32_bf16 v[124:127], v[146:149], v[182:185], v[124:127]
	v_mfma_f32_16x16x32_bf16 v[120:123], v[158:161], v[182:185], v[120:123]
	v_mfma_f32_16x16x32_bf16 v[108:111], v[146:149], v[190:193], v[108:111]
	v_mfma_f32_16x16x32_bf16 v[104:107], v[158:161], v[190:193], v[104:107]
	v_mfma_f32_16x16x32_bf16 v[92:95], v[146:149], v[206:209], v[92:95]
	v_mfma_f32_16x16x32_bf16 v[88:91], v[158:161], v[206:209], v[88:91]
	v_mfma_f32_16x16x32_bf16 v[76:79], v[146:149], v[214:217], v[76:79]
	v_mfma_f32_16x16x32_bf16 v[72:75], v[158:161], v[214:217], v[72:75]
	v_mfma_f32_16x16x32_bf16 v[124:127], v[154:157], v[186:189], v[124:127]
	v_mfma_f32_16x16x32_bf16 v[120:123], v[162:165], v[186:189], v[120:123]
	v_mfma_f32_16x16x32_bf16 v[108:111], v[154:157], v[202:205], v[108:111]
	v_mfma_f32_16x16x32_bf16 v[104:107], v[162:165], v[202:205], v[104:107]
	v_mfma_f32_16x16x32_bf16 v[92:95], v[154:157], v[210:213], v[92:95]
	v_mfma_f32_16x16x32_bf16 v[88:91], v[162:165], v[210:213], v[88:91]
	v_mfma_f32_16x16x32_bf16 v[76:79], v[154:157], v[218:221], v[76:79]
	v_mfma_f32_16x16x32_bf16 v[72:75], v[162:165], v[218:221], v[72:75]
	s_setprio 0
	s_setprio 1
	v_mfma_f32_16x16x32_bf16 v[116:119], v[166:169], v[182:185], v[116:119]
	v_mfma_f32_16x16x32_bf16 v[112:115], v[174:177], v[182:185], v[112:115]
	v_mfma_f32_16x16x32_bf16 v[100:103], v[166:169], v[190:193], v[100:103]
	v_mfma_f32_16x16x32_bf16 v[96:99], v[174:177], v[190:193], v[96:99]
	v_mfma_f32_16x16x32_bf16 v[84:87], v[166:169], v[206:209], v[84:87]
	v_mfma_f32_16x16x32_bf16 v[80:83], v[174:177], v[206:209], v[80:83]
	v_mfma_f32_16x16x32_bf16 v[68:71], v[166:169], v[214:217], v[68:71]
	v_mfma_f32_16x16x32_bf16 v[64:67], v[174:177], v[214:217], v[64:67]
	v_mfma_f32_16x16x32_bf16 v[116:119], v[170:173], v[186:189], v[116:119]
	v_mfma_f32_16x16x32_bf16 v[112:115], v[178:181], v[186:189], v[112:115]
	v_mfma_f32_16x16x32_bf16 v[100:103], v[170:173], v[202:205], v[100:103]
	v_mfma_f32_16x16x32_bf16 v[96:99], v[178:181], v[202:205], v[96:99]
	v_mfma_f32_16x16x32_bf16 v[84:87], v[170:173], v[210:213], v[84:87]
	v_mfma_f32_16x16x32_bf16 v[80:83], v[178:181], v[210:213], v[80:83]
	v_mfma_f32_16x16x32_bf16 v[68:71], v[170:173], v[218:221], v[68:71]
	v_mfma_f32_16x16x32_bf16 v[64:67], v[178:181], v[218:221], v[64:67]
	s_setprio 0
	s_barrier
	s_add_i32 s48, s48, s15
	v_lshl_add_u64 v[194:195], v[194:195], 0, s[10:11]
	s_mov_b32 m0, s48
	ds_read_b128 v[182:185], v153 offset:49152
	ds_read_b128 v[186:189], v153 offset:50176
	ds_read_b128 v[190:193], v153 offset:51200
	ds_read_b128 v[202:205], v153 offset:52224
	ds_read_b128 v[206:209], v153 offset:53248
	ds_read_b128 v[210:213], v153 offset:54272
	ds_read_b128 v[214:217], v153 offset:55296
	ds_read_b128 v[218:221], v153 offset:56320
	global_load_lds_dwordx4 v[194:195], off
	s_add_i32 m0, s48, 0x2000
	s_add_u32 s78, s92, 0x40080
	v_lshl_add_u64 v[194:195], v[222:223], 0, s[10:11]
	s_addc_u32 s79, s93, 0
	s_add_i32 s48, s49, s15
	global_load_lds_dwordx4 v[194:195], off
	v_lshl_add_u64 v[194:195], s[78:79], 0, v[132:133]
	s_mov_b32 m0, s48
	s_nop 0
	global_load_lds_dwordx4 v[194:195], off
	v_lshl_add_u64 v[194:195], s[78:79], 0, v[128:129]
	s_add_i32 m0, s48, 0x2000
	s_nop 0
	global_load_lds_dwordx4 v[194:195], off
	v_lshl_add_u64 v[194:195], v[224:225], 0, s[10:11]
	s_mov_b32 m0, s54
	s_nop 0
	global_load_lds_dwordx4 v[194:195], off
	v_lshl_add_u64 v[194:195], v[226:227], 0, s[10:11]
	s_mov_b32 m0, s55
	s_nop 0
	global_load_lds_dwordx4 v[194:195], off
	s_waitcnt vmcnt(8)
	s_waitcnt lgkmcnt(0)
	s_barrier
	s_setprio 1
	s_waitcnt lgkmcnt(0)
	v_mfma_f32_16x16x32_bf16 v[60:63], v[146:149], v[182:185], v[60:63]
	v_mfma_f32_16x16x32_bf16 v[56:59], v[158:161], v[182:185], v[56:59]
	v_mfma_f32_16x16x32_bf16 v[44:47], v[146:149], v[190:193], v[44:47]
	v_mfma_f32_16x16x32_bf16 v[40:43], v[158:161], v[190:193], v[40:43]
	v_mfma_f32_16x16x32_bf16 v[28:31], v[146:149], v[206:209], v[28:31]
	v_mfma_f32_16x16x32_bf16 v[24:27], v[158:161], v[206:209], v[24:27]
	v_mfma_f32_16x16x32_bf16 v[12:15], v[146:149], v[214:217], v[12:15]
	v_mfma_f32_16x16x32_bf16 v[8:11], v[158:161], v[214:217], v[8:11]
	v_mfma_f32_16x16x32_bf16 v[60:63], v[154:157], v[186:189], v[60:63]
	v_mfma_f32_16x16x32_bf16 v[56:59], v[162:165], v[186:189], v[56:59]
	v_mfma_f32_16x16x32_bf16 v[44:47], v[154:157], v[202:205], v[44:47]
	v_mfma_f32_16x16x32_bf16 v[40:43], v[162:165], v[202:205], v[40:43]
	v_mfma_f32_16x16x32_bf16 v[28:31], v[154:157], v[210:213], v[28:31]
	v_mfma_f32_16x16x32_bf16 v[24:27], v[162:165], v[210:213], v[24:27]
	v_mfma_f32_16x16x32_bf16 v[12:15], v[154:157], v[218:221], v[12:15]
	v_mfma_f32_16x16x32_bf16 v[8:11], v[162:165], v[218:221], v[8:11]
	s_setprio 0
	s_setprio 1
	v_mfma_f32_16x16x32_bf16 v[52:55], v[166:169], v[182:185], v[52:55]
	v_mfma_f32_16x16x32_bf16 v[48:51], v[174:177], v[182:185], v[48:51]
	v_mfma_f32_16x16x32_bf16 v[36:39], v[166:169], v[190:193], v[36:39]
	v_mfma_f32_16x16x32_bf16 v[32:35], v[174:177], v[190:193], v[32:35]
	v_mfma_f32_16x16x32_bf16 v[20:23], v[166:169], v[206:209], v[20:23]
	v_mfma_f32_16x16x32_bf16 v[16:19], v[174:177], v[206:209], v[16:19]
	v_mfma_f32_16x16x32_bf16 v[4:7], v[166:169], v[214:217], v[4:7]
	v_mfma_f32_16x16x32_bf16 v[0:3], v[174:177], v[214:217], v[0:3]
	v_mfma_f32_16x16x32_bf16 v[52:55], v[170:173], v[186:189], v[52:55]
	v_mfma_f32_16x16x32_bf16 v[48:51], v[178:181], v[186:189], v[48:51]
	v_mfma_f32_16x16x32_bf16 v[36:39], v[170:173], v[202:205], v[36:39]
	v_mfma_f32_16x16x32_bf16 v[32:35], v[178:181], v[202:205], v[32:35]
	v_mfma_f32_16x16x32_bf16 v[20:23], v[170:173], v[210:213], v[20:23]
	v_mfma_f32_16x16x32_bf16 v[16:19], v[178:181], v[210:213], v[16:19]
	v_mfma_f32_16x16x32_bf16 v[4:7], v[170:173], v[218:221], v[4:7]
	v_mfma_f32_16x16x32_bf16 v[0:3], v[178:181], v[218:221], v[0:3]
	s_setprio 0
	s_barrier
	s_add_i32 s73, s73, 2
	s_add_u32 s90, s90, 0x100
	s_addc_u32 s91, s91, 0
	s_add_u32 s71, s71, 0x100
	s_addc_u32 s72, s72, 0

.LBB0_965:
	s_ashr_i32 s19, s18, 31
	s_lshl_b64 s[12:13], s[18:19], 19
	s_add_u32 s20, s34, s12
	s_addc_u32 s21, s35, s13
	s_and_b64 s[12:13], s[0:1], exec
	s_cselect_b32 s12, s21, s27
	s_cselect_b32 s13, s20, s26
	s_ashr_i32 s17, s16, 31
	s_lshl_b64 s[22:23], s[16:17], 19
	s_add_u32 s22, s50, s22
	s_addc_u32 s23, s51, s23
	s_and_b64 s[48:49], s[0:1], exec
	s_cselect_b32 s17, s23, s29
	s_cselect_b32 s19, s22, s28
	s_add_u32 s26, s26, 0x40080
	s_addc_u32 s27, s27, 0
	s_add_u32 s61, s28, 0x100
	s_addc_u32 s62, s29, 0
	s_mov_b32 s63, -2
	ds_read_b128 v[146:149], v151
	ds_read_b128 v[154:157], v151 offset:1024
	ds_read_b128 v[158:161], v151 offset:2048
	ds_read_b128 v[162:165], v151 offset:3072
	ds_read_b128 v[166:169], v152
	ds_read_b128 v[170:173], v152 offset:1024
	ds_read_b128 v[174:177], v152 offset:2048
	ds_read_b128 v[178:181], v152 offset:3072
	s_add_u32 s28, s26, 0xfffc0080
	s_addc_u32 s29, s27, -1
	s_cmp_eq_u32 s63, 12
	s_cselect_b32 s53, s12, s29
	s_cselect_b32 s52, s13, s28
	s_cselect_b32 s29, s17, s62
	s_cselect_b32 s28, s19, s61
	v_lshl_add_u64 v[194:195], s[26:27], 0, v[138:139]
	s_add_i32 m0, s14, 0xc000
	ds_read_b128 v[182:185], v153
	ds_read_b128 v[186:189], v153 offset:1024
	ds_read_b128 v[190:193], v153 offset:2048
	ds_read_b128 v[198:201], v153 offset:3072
	ds_read_b128 v[202:205], v153 offset:4096
	ds_read_b128 v[206:209], v153 offset:5120
	ds_read_b128 v[210:213], v153 offset:6144
	ds_read_b128 v[214:217], v153 offset:7168
	global_load_lds_dwordx4 v[194:195], off
	v_lshl_add_u64 v[194:195], s[26:27], 0, v[140:141]
	s_add_i32 m0, s14, 0xe000
	s_nop 0
	global_load_lds_dwordx4 v[194:195], off
	s_waitcnt vmcnt(8)
	s_waitcnt lgkmcnt(0)
	s_barrier
	s_setprio 1
	s_waitcnt lgkmcnt(0)
	v_mfma_f32_16x16x32_bf16 v[124:127], v[146:149], v[182:185], 0
	v_mfma_f32_16x16x32_bf16 v[120:123], v[158:161], v[182:185], 0
	v_mfma_f32_16x16x32_bf16 v[108:111], v[146:149], v[190:193], 0
	v_mfma_f32_16x16x32_bf16 v[104:107], v[158:161], v[190:193], 0
	v_mfma_f32_16x16x32_bf16 v[92:95], v[146:149], v[202:205], 0
	v_mfma_f32_16x16x32_bf16 v[88:91], v[158:161], v[202:205], 0
	v_mfma_f32_16x16x32_bf16 v[76:79], v[146:149], v[210:213], 0
	v_mfma_f32_16x16x32_bf16 v[72:75], v[158:161], v[210:213], 0
	v_mfma_f32_16x16x32_bf16 v[124:127], v[154:157], v[186:189], v[124:127]
	v_mfma_f32_16x16x32_bf16 v[120:123], v[162:165], v[186:189], v[120:123]
	v_mfma_f32_16x16x32_bf16 v[108:111], v[154:157], v[198:201], v[108:111]
	v_mfma_f32_16x16x32_bf16 v[104:107], v[162:165], v[198:201], v[104:107]
	v_mfma_f32_16x16x32_bf16 v[92:95], v[154:157], v[206:209], v[92:95]
	v_mfma_f32_16x16x32_bf16 v[88:91], v[162:165], v[206:209], v[88:91]
	v_mfma_f32_16x16x32_bf16 v[76:79], v[154:157], v[214:217], v[76:79]
	v_mfma_f32_16x16x32_bf16 v[72:75], v[162:165], v[214:217], v[72:75]
	s_setprio 0
	s_setprio 1
	v_mfma_f32_16x16x32_bf16 v[116:119], v[166:169], v[182:185], 0
	v_mfma_f32_16x16x32_bf16 v[112:115], v[174:177], v[182:185], 0
	v_mfma_f32_16x16x32_bf16 v[100:103], v[166:169], v[190:193], 0
	v_mfma_f32_16x16x32_bf16 v[96:99], v[174:177], v[190:193], 0
	v_mfma_f32_16x16x32_bf16 v[84:87], v[166:169], v[202:205], 0
	v_mfma_f32_16x16x32_bf16 v[80:83], v[174:177], v[202:205], 0
	v_mfma_f32_16x16x32_bf16 v[68:71], v[166:169], v[210:213], 0
	v_mfma_f32_16x16x32_bf16 v[64:67], v[174:177], v[210:213], 0
	v_mfma_f32_16x16x32_bf16 v[116:119], v[170:173], v[186:189], v[116:119]
	v_mfma_f32_16x16x32_bf16 v[112:115], v[178:181], v[186:189], v[112:115]
	v_mfma_f32_16x16x32_bf16 v[100:103], v[170:173], v[198:201], v[100:103]
	v_mfma_f32_16x16x32_bf16 v[96:99], v[178:181], v[198:201], v[96:99]
	v_mfma_f32_16x16x32_bf16 v[84:87], v[170:173], v[206:209], v[84:87]
	v_mfma_f32_16x16x32_bf16 v[80:83], v[178:181], v[206:209], v[80:83]
	v_mfma_f32_16x16x32_bf16 v[68:71], v[170:173], v[214:217], v[68:71]
	v_mfma_f32_16x16x32_bf16 v[64:67], v[178:181], v[214:217], v[64:67]
	s_setprio 0
	s_barrier
	s_add_i32 s48, s58, s3
	v_lshl_add_u64 v[194:195], s[28:29], 0, v[130:131]
	s_mov_b32 m0, s48
	ds_read_b128 v[182:185], v153 offset:16384
	ds_read_b128 v[186:189], v153 offset:17408
	ds_read_b128 v[190:193], v153 offset:18432
	ds_read_b128 v[198:201], v153 offset:19456
	ds_read_b128 v[202:205], v153 offset:20480
	ds_read_b128 v[206:209], v153 offset:21504
	ds_read_b128 v[210:213], v153 offset:22528
	ds_read_b128 v[214:217], v153 offset:23552
	global_load_lds_dwordx4 v[194:195], off
	s_add_i32 m0, s48, 0x2000
	s_add_u32 s48, s28, 0x40000
	v_lshl_add_u64 v[218:219], s[28:29], 0, v[134:135]
	s_addc_u32 s49, s29, 0
	s_add_i32 s64, s59, s3
	global_load_lds_dwordx4 v[218:219], off
	v_lshl_add_u64 v[220:221], s[48:49], 0, v[130:131]
	s_mov_b32 m0, s64
	v_lshl_add_u64 v[222:223], s[52:53], 0, v[132:133]
	global_load_lds_dwordx4 v[220:221], off
	v_lshl_add_u64 v[220:221], s[48:49], 0, v[134:135]
	s_add_i32 m0, s64, 0x2000
	s_nop 0
	global_load_lds_dwordx4 v[220:221], off
	v_lshl_add_u64 v[220:221], s[52:53], 0, v[128:129]
	s_mov_b32 m0, s14
	s_nop 0
	global_load_lds_dwordx4 v[220:221], off
	s_mov_b32 m0, s15
	s_nop 0
	global_load_lds_dwordx4 v[222:223], off
	s_waitcnt vmcnt(8)
	s_waitcnt lgkmcnt(0)
	s_barrier
	s_setprio 1
	s_waitcnt lgkmcnt(0)
	v_mfma_f32_16x16x32_bf16 v[60:63], v[146:149], v[182:185], 0
	v_mfma_f32_16x16x32_bf16 v[56:59], v[158:161], v[182:185], 0
	v_mfma_f32_16x16x32_bf16 v[44:47], v[146:149], v[190:193], 0
	v_mfma_f32_16x16x32_bf16 v[40:43], v[158:161], v[190:193], 0
	v_mfma_f32_16x16x32_bf16 v[28:31], v[146:149], v[202:205], 0
	v_mfma_f32_16x16x32_bf16 v[24:27], v[158:161], v[202:205], 0
	v_mfma_f32_16x16x32_bf16 v[12:15], v[146:149], v[210:213], 0
	v_mfma_f32_16x16x32_bf16 v[8:11], v[158:161], v[210:213], 0
	v_mfma_f32_16x16x32_bf16 v[60:63], v[154:157], v[186:189], v[60:63]
	v_mfma_f32_16x16x32_bf16 v[56:59], v[162:165], v[186:189], v[56:59]
	v_mfma_f32_16x16x32_bf16 v[44:47], v[154:157], v[198:201], v[44:47]
	v_mfma_f32_16x16x32_bf16 v[40:43], v[162:165], v[198:201], v[40:43]
	v_mfma_f32_16x16x32_bf16 v[28:31], v[154:157], v[206:209], v[28:31]
	v_mfma_f32_16x16x32_bf16 v[24:27], v[162:165], v[206:209], v[24:27]
	v_mfma_f32_16x16x32_bf16 v[12:15], v[154:157], v[214:217], v[12:15]
	v_mfma_f32_16x16x32_bf16 v[8:11], v[162:165], v[214:217], v[8:11]
	s_setprio 0
	s_setprio 1
	v_mfma_f32_16x16x32_bf16 v[52:55], v[166:169], v[182:185], 0
	v_mfma_f32_16x16x32_bf16 v[48:51], v[174:177], v[182:185], 0
	v_mfma_f32_16x16x32_bf16 v[36:39], v[166:169], v[190:193], 0
	v_mfma_f32_16x16x32_bf16 v[32:35], v[174:177], v[190:193], 0
	v_mfma_f32_16x16x32_bf16 v[20:23], v[166:169], v[202:205], 0
	v_mfma_f32_16x16x32_bf16 v[16:19], v[174:177], v[202:205], 0
	v_mfma_f32_16x16x32_bf16 v[4:7], v[166:169], v[210:213], 0
	v_mfma_f32_16x16x32_bf16 v[0:3], v[174:177], v[210:213], 0
	v_mfma_f32_16x16x32_bf16 v[52:55], v[170:173], v[186:189], v[52:55]
	v_mfma_f32_16x16x32_bf16 v[48:51], v[178:181], v[186:189], v[48:51]
	v_mfma_f32_16x16x32_bf16 v[36:39], v[170:173], v[198:201], v[36:39]
	v_mfma_f32_16x16x32_bf16 v[32:35], v[178:181], v[198:201], v[32:35]
	v_mfma_f32_16x16x32_bf16 v[20:23], v[170:173], v[206:209], v[20:23]
	v_mfma_f32_16x16x32_bf16 v[16:19], v[178:181], v[206:209], v[16:19]
	v_mfma_f32_16x16x32_bf16 v[4:7], v[170:173], v[214:217], v[4:7]
	v_mfma_f32_16x16x32_bf16 v[0:3], v[178:181], v[214:217], v[0:3]
	s_setprio 0
	s_barrier
	s_add_i32 s64, 0, 0x18000
	s_add_i32 s65, 0, 0x1c000
	v_add_u32_e32 v162, s64, v150
	v_add_u32_e32 v178, s65, v150
	ds_read_b128 v[146:149], v162
	ds_read_b128 v[154:157], v162 offset:1024
	ds_read_b128 v[158:161], v162 offset:2048
	ds_read_b128 v[162:165], v162 offset:3072
	ds_read_b128 v[166:169], v178
	ds_read_b128 v[170:173], v178 offset:1024
	ds_read_b128 v[174:177], v178 offset:2048
	ds_read_b128 v[178:181], v178 offset:3072
	s_add_u32 s48, s52, 0x40000
	s_addc_u32 s49, s53, 0
	s_mov_b32 m0, s25
	v_lshl_add_u64 v[224:225], s[48:49], 0, v[128:129]
	ds_read_b128 v[182:185], v153 offset:32768
	ds_read_b128 v[186:189], v153 offset:33792
	ds_read_b128 v[190:193], v153 offset:34816
	ds_read_b128 v[198:201], v153 offset:35840
	ds_read_b128 v[202:205], v153 offset:36864
	ds_read_b128 v[206:209], v153 offset:37888
	ds_read_b128 v[210:213], v153 offset:38912
	ds_read_b128 v[214:217], v153 offset:39936
	global_load_lds_dwordx4 v[224:225], off
	v_lshl_add_u64 v[224:225], s[48:49], 0, v[132:133]
	s_mov_b32 m0, s46
	s_nop 0
	global_load_lds_dwordx4 v[224:225], off
	s_waitcnt vmcnt(8)
	s_waitcnt lgkmcnt(0)
	s_barrier
	s_setprio 1
	s_waitcnt lgkmcnt(0)
	v_mfma_f32_16x16x32_bf16 v[124:127], v[146:149], v[182:185], v[124:127]
	v_mfma_f32_16x16x32_bf16 v[120:123], v[158:161], v[182:185], v[120:123]
	v_mfma_f32_16x16x32_bf16 v[108:111], v[146:149], v[190:193], v[108:111]
	v_mfma_f32_16x16x32_bf16 v[104:107], v[158:161], v[190:193], v[104:107]
	v_mfma_f32_16x16x32_bf16 v[92:95], v[146:149], v[202:205], v[92:95]
	v_mfma_f32_16x16x32_bf16 v[88:91], v[158:161], v[202:205], v[88:91]
	v_mfma_f32_16x16x32_bf16 v[76:79], v[146:149], v[210:213], v[76:79]
	v_mfma_f32_16x16x32_bf16 v[72:75], v[158:161], v[210:213], v[72:75]
	v_mfma_f32_16x16x32_bf16 v[124:127], v[154:157], v[186:189], v[124:127]
	v_mfma_f32_16x16x32_bf16 v[120:123], v[162:165], v[186:189], v[120:123]
	v_mfma_f32_16x16x32_bf16 v[108:111], v[154:157], v[198:201], v[108:111]
	v_mfma_f32_16x16x32_bf16 v[104:107], v[162:165], v[198:201], v[104:107]
	v_mfma_f32_16x16x32_bf16 v[92:95], v[154:157], v[206:209], v[92:95]
	v_mfma_f32_16x16x32_bf16 v[88:91], v[162:165], v[206:209], v[88:91]
	v_mfma_f32_16x16x32_bf16 v[76:79], v[154:157], v[214:217], v[76:79]
	v_mfma_f32_16x16x32_bf16 v[72:75], v[162:165], v[214:217], v[72:75]
	s_setprio 0
	s_setprio 1
	v_mfma_f32_16x16x32_bf16 v[116:119], v[166:169], v[182:185], v[116:119]
	v_mfma_f32_16x16x32_bf16 v[112:115], v[174:177], v[182:185], v[112:115]
	v_mfma_f32_16x16x32_bf16 v[100:103], v[166:169], v[190:193], v[100:103]
	v_mfma_f32_16x16x32_bf16 v[96:99], v[174:177], v[190:193], v[96:99]
	v_mfma_f32_16x16x32_bf16 v[84:87], v[166:169], v[202:205], v[84:87]
	v_mfma_f32_16x16x32_bf16 v[80:83], v[174:177], v[202:205], v[80:83]
	v_mfma_f32_16x16x32_bf16 v[68:71], v[166:169], v[210:213], v[68:71]
	v_mfma_f32_16x16x32_bf16 v[64:67], v[174:177], v[210:213], v[64:67]
	v_mfma_f32_16x16x32_bf16 v[116:119], v[170:173], v[186:189], v[116:119]
	v_mfma_f32_16x16x32_bf16 v[112:115], v[178:181], v[186:189], v[112:115]
	v_mfma_f32_16x16x32_bf16 v[100:103], v[170:173], v[198:201], v[100:103]
	v_mfma_f32_16x16x32_bf16 v[96:99], v[178:181], v[198:201], v[96:99]
	v_mfma_f32_16x16x32_bf16 v[84:87], v[170:173], v[206:209], v[84:87]
	v_mfma_f32_16x16x32_bf16 v[80:83], v[178:181], v[206:209], v[80:83]
	v_mfma_f32_16x16x32_bf16 v[68:71], v[170:173], v[214:217], v[68:71]
	v_mfma_f32_16x16x32_bf16 v[64:67], v[178:181], v[214:217], v[64:67]
	s_setprio 0
	s_barrier
	s_add_i32 s48, s64, s3
	v_lshl_add_u64 v[194:195], v[194:195], 0, s[8:9]
	s_mov_b32 m0, s48
	ds_read_b128 v[182:185], v153 offset:49152
	ds_read_b128 v[186:189], v153 offset:50176
	ds_read_b128 v[190:193], v153 offset:51200
	ds_read_b128 v[198:201], v153 offset:52224
	ds_read_b128 v[202:205], v153 offset:53248
	ds_read_b128 v[206:209], v153 offset:54272
	ds_read_b128 v[210:213], v153 offset:55296
	ds_read_b128 v[214:217], v153 offset:56320
	global_load_lds_dwordx4 v[194:195], off
	s_add_i32 m0, s48, 0x2000
	s_add_u32 s28, s28, 0x40080
	v_lshl_add_u64 v[194:195], v[218:219], 0, s[8:9]
	s_addc_u32 s29, s29, 0
	s_add_i32 s48, s65, s3
	global_load_lds_dwordx4 v[194:195], off
	v_lshl_add_u64 v[194:195], s[28:29], 0, v[130:131]
	s_mov_b32 m0, s48
	s_nop 0
	global_load_lds_dwordx4 v[194:195], off
	v_lshl_add_u64 v[194:195], s[28:29], 0, v[134:135]
	s_add_i32 m0, s48, 0x2000
	s_nop 0
	global_load_lds_dwordx4 v[194:195], off
	v_lshl_add_u64 v[194:195], v[220:221], 0, s[8:9]
	s_mov_b32 m0, s54
	s_nop 0
	global_load_lds_dwordx4 v[194:195], off
	v_lshl_add_u64 v[194:195], v[222:223], 0, s[8:9]
	s_mov_b32 m0, s55
	s_nop 0
	global_load_lds_dwordx4 v[194:195], off
	s_waitcnt vmcnt(8)
	s_waitcnt lgkmcnt(0)
	s_barrier
	s_setprio 1
	s_waitcnt lgkmcnt(0)
	v_mfma_f32_16x16x32_bf16 v[60:63], v[146:149], v[182:185], v[60:63]
	v_mfma_f32_16x16x32_bf16 v[56:59], v[158:161], v[182:185], v[56:59]
	v_mfma_f32_16x16x32_bf16 v[44:47], v[146:149], v[190:193], v[44:47]
	v_mfma_f32_16x16x32_bf16 v[40:43], v[158:161], v[190:193], v[40:43]
	v_mfma_f32_16x16x32_bf16 v[28:31], v[146:149], v[202:205], v[28:31]
	v_mfma_f32_16x16x32_bf16 v[24:27], v[158:161], v[202:205], v[24:27]
	v_mfma_f32_16x16x32_bf16 v[12:15], v[146:149], v[210:213], v[12:15]
	v_mfma_f32_16x16x32_bf16 v[8:11], v[158:161], v[210:213], v[8:11]
	v_mfma_f32_16x16x32_bf16 v[60:63], v[154:157], v[186:189], v[60:63]
	v_mfma_f32_16x16x32_bf16 v[56:59], v[162:165], v[186:189], v[56:59]
	v_mfma_f32_16x16x32_bf16 v[44:47], v[154:157], v[198:201], v[44:47]
	v_mfma_f32_16x16x32_bf16 v[40:43], v[162:165], v[198:201], v[40:43]
	v_mfma_f32_16x16x32_bf16 v[28:31], v[154:157], v[206:209], v[28:31]
	v_mfma_f32_16x16x32_bf16 v[24:27], v[162:165], v[206:209], v[24:27]
	v_mfma_f32_16x16x32_bf16 v[12:15], v[154:157], v[214:217], v[12:15]
	v_mfma_f32_16x16x32_bf16 v[8:11], v[162:165], v[214:217], v[8:11]
	s_setprio 0
	s_setprio 1
	v_mfma_f32_16x16x32_bf16 v[52:55], v[166:169], v[182:185], v[52:55]
	v_mfma_f32_16x16x32_bf16 v[48:51], v[174:177], v[182:185], v[48:51]
	v_mfma_f32_16x16x32_bf16 v[36:39], v[166:169], v[190:193], v[36:39]
	v_mfma_f32_16x16x32_bf16 v[32:35], v[174:177], v[190:193], v[32:35]
	v_mfma_f32_16x16x32_bf16 v[20:23], v[166:169], v[202:205], v[20:23]
	v_mfma_f32_16x16x32_bf16 v[16:19], v[174:177], v[202:205], v[16:19]
	v_mfma_f32_16x16x32_bf16 v[4:7], v[166:169], v[210:213], v[4:7]
	v_mfma_f32_16x16x32_bf16 v[0:3], v[174:177], v[210:213], v[0:3]
	v_mfma_f32_16x16x32_bf16 v[52:55], v[170:173], v[186:189], v[52:55]
	v_mfma_f32_16x16x32_bf16 v[48:51], v[178:181], v[186:189], v[48:51]
	v_mfma_f32_16x16x32_bf16 v[36:39], v[170:173], v[198:201], v[36:39]
	v_mfma_f32_16x16x32_bf16 v[32:35], v[178:181], v[198:201], v[32:35]
	v_mfma_f32_16x16x32_bf16 v[20:23], v[170:173], v[206:209], v[20:23]
	v_mfma_f32_16x16x32_bf16 v[16:19], v[178:181], v[206:209], v[16:19]
	v_mfma_f32_16x16x32_bf16 v[4:7], v[170:173], v[214:217], v[4:7]
	v_mfma_f32_16x16x32_bf16 v[0:3], v[178:181], v[214:217], v[0:3]
	s_setprio 0
	s_barrier
	s_add_i32 s63, s63, 2
	s_add_u32 s26, s26, 0x100
	s_addc_u32 s27, s27, 0
	s_add_u32 s61, s61, 0x100
	s_addc_u32 s62, s62, 0

.LBB0_1036:
	s_ashr_i32 s49, s48, 31
	s_lshl_b64 s[12:13], s[48:49], 19
	s_add_u32 s52, s42, s12
	s_addc_u32 s53, s43, s13
	s_and_b64 s[12:13], s[4:5], exec
	s_cselect_b32 s12, s53, s61
	s_cselect_b32 s13, s52, s60
	s_ashr_i32 s45, s44, 31
	s_lshl_b64 s[54:55], s[44:45], 19
	s_add_u32 s54, s40, s54
	s_addc_u32 s55, s41, s55
	s_and_b64 s[64:65], s[4:5], exec
	s_cselect_b32 s45, s55, s63
	s_cselect_b32 s49, s54, s62
	s_add_u32 s60, s60, 0x40080
	s_addc_u32 s61, s61, 0
	s_add_u32 s75, s62, 0x100
	s_addc_u32 s76, s63, 0
	s_mov_b32 s77, -2
	ds_read_b128 v[144:147], v165
	ds_read_b128 v[148:151], v165 offset:1024
	ds_read_b128 v[152:155], v165 offset:2048
	ds_read_b128 v[156:159], v165 offset:3072
	ds_read_b128 v[170:173], v166
	ds_read_b128 v[174:177], v166 offset:1024
	ds_read_b128 v[178:181], v166 offset:2048
	ds_read_b128 v[182:185], v166 offset:3072
	s_add_u32 s62, s60, 0xfffc0080
	s_addc_u32 s63, s61, -1
	s_cmp_eq_u32 s77, 12
	s_cselect_b32 s65, s12, s63
	s_cselect_b32 s64, s13, s62
	s_cselect_b32 s63, s45, s76
	s_cselect_b32 s62, s49, s75
	v_lshl_add_u64 v[160:161], s[60:61], 0, v[136:137]
	s_add_i32 m0, s3, 0xc000
	ds_read_b128 v[186:189], v167
	ds_read_b128 v[190:193], v167 offset:1024
	ds_read_b128 v[198:201], v167 offset:2048
	ds_read_b128 v[202:205], v167 offset:3072
	ds_read_b128 v[206:209], v167 offset:4096
	ds_read_b128 v[210:213], v167 offset:5120
	ds_read_b128 v[214:217], v167 offset:6144
	ds_read_b128 v[218:221], v167 offset:7168
	global_load_lds_dwordx4 v[160:161], off
	v_lshl_add_u64 v[160:161], s[60:61], 0, v[138:139]
	s_add_i32 m0, s3, 0xe000
	s_nop 0
	global_load_lds_dwordx4 v[160:161], off
	s_waitcnt vmcnt(8)
	s_waitcnt lgkmcnt(0)
	s_barrier
	s_setprio 1
	s_waitcnt lgkmcnt(0)
	v_mfma_f32_16x16x32_bf16 v[124:127], v[144:147], v[186:189], 0
	v_mfma_f32_16x16x32_bf16 v[120:123], v[152:155], v[186:189], 0
	v_mfma_f32_16x16x32_bf16 v[108:111], v[144:147], v[198:201], 0
	v_mfma_f32_16x16x32_bf16 v[104:107], v[152:155], v[198:201], 0
	v_mfma_f32_16x16x32_bf16 v[92:95], v[144:147], v[206:209], 0
	v_mfma_f32_16x16x32_bf16 v[88:91], v[152:155], v[206:209], 0
	v_mfma_f32_16x16x32_bf16 v[76:79], v[144:147], v[214:217], 0
	v_mfma_f32_16x16x32_bf16 v[72:75], v[152:155], v[214:217], 0
	v_mfma_f32_16x16x32_bf16 v[124:127], v[148:151], v[190:193], v[124:127]
	v_mfma_f32_16x16x32_bf16 v[120:123], v[156:159], v[190:193], v[120:123]
	v_mfma_f32_16x16x32_bf16 v[108:111], v[148:151], v[202:205], v[108:111]
	v_mfma_f32_16x16x32_bf16 v[104:107], v[156:159], v[202:205], v[104:107]
	v_mfma_f32_16x16x32_bf16 v[92:95], v[148:151], v[210:213], v[92:95]
	v_mfma_f32_16x16x32_bf16 v[88:91], v[156:159], v[210:213], v[88:91]
	v_mfma_f32_16x16x32_bf16 v[76:79], v[148:151], v[218:221], v[76:79]
	v_mfma_f32_16x16x32_bf16 v[72:75], v[156:159], v[218:221], v[72:75]
	s_setprio 0
	s_setprio 1
	v_mfma_f32_16x16x32_bf16 v[116:119], v[170:173], v[186:189], 0
	v_mfma_f32_16x16x32_bf16 v[112:115], v[178:181], v[186:189], 0
	v_mfma_f32_16x16x32_bf16 v[100:103], v[170:173], v[198:201], 0
	v_mfma_f32_16x16x32_bf16 v[96:99], v[178:181], v[198:201], 0
	v_mfma_f32_16x16x32_bf16 v[84:87], v[170:173], v[206:209], 0
	v_mfma_f32_16x16x32_bf16 v[80:83], v[178:181], v[206:209], 0
	v_mfma_f32_16x16x32_bf16 v[68:71], v[170:173], v[214:217], 0
	v_mfma_f32_16x16x32_bf16 v[64:67], v[178:181], v[214:217], 0
	v_mfma_f32_16x16x32_bf16 v[116:119], v[174:177], v[190:193], v[116:119]
	v_mfma_f32_16x16x32_bf16 v[112:115], v[182:185], v[190:193], v[112:115]
	v_mfma_f32_16x16x32_bf16 v[100:103], v[174:177], v[202:205], v[100:103]
	v_mfma_f32_16x16x32_bf16 v[96:99], v[182:185], v[202:205], v[96:99]
	v_mfma_f32_16x16x32_bf16 v[84:87], v[174:177], v[210:213], v[84:87]
	v_mfma_f32_16x16x32_bf16 v[80:83], v[182:185], v[210:213], v[80:83]
	v_mfma_f32_16x16x32_bf16 v[68:71], v[174:177], v[218:221], v[68:71]
	v_mfma_f32_16x16x32_bf16 v[64:67], v[182:185], v[218:221], v[64:67]
	s_setprio 0
	s_barrier
	s_add_i32 s78, s73, s2
	v_lshl_add_u64 v[160:161], s[62:63], 0, v[130:131]
	s_mov_b32 m0, s78
	ds_read_b128 v[186:189], v167 offset:16384
	ds_read_b128 v[190:193], v167 offset:17408
	ds_read_b128 v[198:201], v167 offset:18432
	ds_read_b128 v[202:205], v167 offset:19456
	ds_read_b128 v[206:209], v167 offset:20480
	ds_read_b128 v[210:213], v167 offset:21504
	ds_read_b128 v[214:217], v167 offset:22528
	ds_read_b128 v[218:221], v167 offset:23552
	global_load_lds_dwordx4 v[160:161], off
	s_add_i32 m0, s78, 0x2000
	s_add_u32 s78, s62, 0x40000
	v_lshl_add_u64 v[194:195], s[62:63], 0, v[134:135]
	s_addc_u32 s79, s63, 0
	s_add_i32 s80, s74, s2
	global_load_lds_dwordx4 v[194:195], off
	v_lshl_add_u64 v[222:223], s[78:79], 0, v[130:131]
	s_mov_b32 m0, s80
	v_lshl_add_u64 v[224:225], s[64:65], 0, v[132:133]
	global_load_lds_dwordx4 v[222:223], off
	v_lshl_add_u64 v[222:223], s[78:79], 0, v[134:135]
	s_add_i32 m0, s80, 0x2000
	s_nop 0
	global_load_lds_dwordx4 v[222:223], off
	v_lshl_add_u64 v[222:223], s[64:65], 0, v[128:129]
	s_mov_b32 m0, s3
	s_nop 0
	global_load_lds_dwordx4 v[222:223], off
	s_mov_b32 m0, s14
	s_nop 0
	global_load_lds_dwordx4 v[224:225], off
	s_waitcnt vmcnt(8)
	s_waitcnt lgkmcnt(0)
	s_barrier
	s_setprio 1
	s_waitcnt lgkmcnt(0)
	v_mfma_f32_16x16x32_bf16 v[60:63], v[144:147], v[186:189], 0
	v_mfma_f32_16x16x32_bf16 v[56:59], v[152:155], v[186:189], 0
	v_mfma_f32_16x16x32_bf16 v[44:47], v[144:147], v[198:201], 0
	v_mfma_f32_16x16x32_bf16 v[40:43], v[152:155], v[198:201], 0
	v_mfma_f32_16x16x32_bf16 v[28:31], v[144:147], v[206:209], 0
	v_mfma_f32_16x16x32_bf16 v[24:27], v[152:155], v[206:209], 0
	v_mfma_f32_16x16x32_bf16 v[12:15], v[144:147], v[214:217], 0
	v_mfma_f32_16x16x32_bf16 v[8:11], v[152:155], v[214:217], 0
	v_mfma_f32_16x16x32_bf16 v[60:63], v[148:151], v[190:193], v[60:63]
	v_mfma_f32_16x16x32_bf16 v[56:59], v[156:159], v[190:193], v[56:59]
	v_mfma_f32_16x16x32_bf16 v[44:47], v[148:151], v[202:205], v[44:47]
	v_mfma_f32_16x16x32_bf16 v[40:43], v[156:159], v[202:205], v[40:43]
	v_mfma_f32_16x16x32_bf16 v[28:31], v[148:151], v[210:213], v[28:31]
	v_mfma_f32_16x16x32_bf16 v[24:27], v[156:159], v[210:213], v[24:27]
	v_mfma_f32_16x16x32_bf16 v[12:15], v[148:151], v[218:221], v[12:15]
	v_mfma_f32_16x16x32_bf16 v[8:11], v[156:159], v[218:221], v[8:11]
	s_setprio 0
	s_setprio 1
	v_mfma_f32_16x16x32_bf16 v[52:55], v[170:173], v[186:189], 0
	v_mfma_f32_16x16x32_bf16 v[48:51], v[178:181], v[186:189], 0
	v_mfma_f32_16x16x32_bf16 v[36:39], v[170:173], v[198:201], 0
	v_mfma_f32_16x16x32_bf16 v[32:35], v[178:181], v[198:201], 0
	v_mfma_f32_16x16x32_bf16 v[20:23], v[170:173], v[206:209], 0
	v_mfma_f32_16x16x32_bf16 v[16:19], v[178:181], v[206:209], 0
	v_mfma_f32_16x16x32_bf16 v[4:7], v[170:173], v[214:217], 0
	v_mfma_f32_16x16x32_bf16 v[0:3], v[178:181], v[214:217], 0
	v_mfma_f32_16x16x32_bf16 v[52:55], v[174:177], v[190:193], v[52:55]
	v_mfma_f32_16x16x32_bf16 v[48:51], v[182:185], v[190:193], v[48:51]
	v_mfma_f32_16x16x32_bf16 v[36:39], v[174:177], v[202:205], v[36:39]
	v_mfma_f32_16x16x32_bf16 v[32:35], v[182:185], v[202:205], v[32:35]
	v_mfma_f32_16x16x32_bf16 v[20:23], v[174:177], v[210:213], v[20:23]
	v_mfma_f32_16x16x32_bf16 v[16:19], v[182:185], v[210:213], v[16:19]
	v_mfma_f32_16x16x32_bf16 v[4:7], v[174:177], v[218:221], v[4:7]
	v_mfma_f32_16x16x32_bf16 v[0:3], v[182:185], v[218:221], v[0:3]
	s_setprio 0
	s_barrier
	s_add_i32 s78, 0, 0x18000
	s_add_i32 s79, 0, 0x1c000
	v_add_u32_e32 v156, s78, v163
	v_add_u32_e32 v169, s79, v163
	ds_read_b128 v[144:147], v156
	ds_read_b128 v[148:151], v156 offset:1024
	ds_read_b128 v[152:155], v156 offset:2048
	ds_read_b128 v[156:159], v156 offset:3072
	ds_read_b128 v[170:173], v169
	ds_read_b128 v[174:177], v169 offset:1024
	ds_read_b128 v[178:181], v169 offset:2048
	ds_read_b128 v[182:185], v169 offset:3072
	s_add_u32 s64, s64, 0x40000
	s_addc_u32 s65, s65, 0
	s_mov_b32 m0, s15
	v_lshl_add_u64 v[226:227], s[64:65], 0, v[128:129]
	ds_read_b128 v[186:189], v167 offset:32768
	ds_read_b128 v[190:193], v167 offset:33792
	ds_read_b128 v[198:201], v167 offset:34816
	ds_read_b128 v[202:205], v167 offset:35840
	ds_read_b128 v[206:209], v167 offset:36864
	ds_read_b128 v[210:213], v167 offset:37888
	ds_read_b128 v[214:217], v167 offset:38912
	ds_read_b128 v[218:221], v167 offset:39936
	global_load_lds_dwordx4 v[226:227], off
	v_lshl_add_u64 v[226:227], s[64:65], 0, v[132:133]
	s_mov_b32 m0, s46
	s_nop 0
	global_load_lds_dwordx4 v[226:227], off
	s_waitcnt vmcnt(8)
	s_waitcnt lgkmcnt(0)
	s_barrier
	s_setprio 1
	s_waitcnt lgkmcnt(0)
	v_mfma_f32_16x16x32_bf16 v[124:127], v[144:147], v[186:189], v[124:127]
	v_mfma_f32_16x16x32_bf16 v[120:123], v[152:155], v[186:189], v[120:123]
	v_mfma_f32_16x16x32_bf16 v[108:111], v[144:147], v[198:201], v[108:111]
	v_mfma_f32_16x16x32_bf16 v[104:107], v[152:155], v[198:201], v[104:107]
	v_mfma_f32_16x16x32_bf16 v[92:95], v[144:147], v[206:209], v[92:95]
	v_mfma_f32_16x16x32_bf16 v[88:91], v[152:155], v[206:209], v[88:91]
	v_mfma_f32_16x16x32_bf16 v[76:79], v[144:147], v[214:217], v[76:79]
	v_mfma_f32_16x16x32_bf16 v[72:75], v[152:155], v[214:217], v[72:75]
	v_mfma_f32_16x16x32_bf16 v[124:127], v[148:151], v[190:193], v[124:127]
	v_mfma_f32_16x16x32_bf16 v[120:123], v[156:159], v[190:193], v[120:123]
	v_mfma_f32_16x16x32_bf16 v[108:111], v[148:151], v[202:205], v[108:111]
	v_mfma_f32_16x16x32_bf16 v[104:107], v[156:159], v[202:205], v[104:107]
	v_mfma_f32_16x16x32_bf16 v[92:95], v[148:151], v[210:213], v[92:95]
	v_mfma_f32_16x16x32_bf16 v[88:91], v[156:159], v[210:213], v[88:91]
	v_mfma_f32_16x16x32_bf16 v[76:79], v[148:151], v[218:221], v[76:79]
	v_mfma_f32_16x16x32_bf16 v[72:75], v[156:159], v[218:221], v[72:75]
	s_setprio 0
	s_setprio 1
	v_mfma_f32_16x16x32_bf16 v[116:119], v[170:173], v[186:189], v[116:119]
	v_mfma_f32_16x16x32_bf16 v[112:115], v[178:181], v[186:189], v[112:115]
	v_mfma_f32_16x16x32_bf16 v[100:103], v[170:173], v[198:201], v[100:103]
	v_mfma_f32_16x16x32_bf16 v[96:99], v[178:181], v[198:201], v[96:99]
	v_mfma_f32_16x16x32_bf16 v[84:87], v[170:173], v[206:209], v[84:87]
	v_mfma_f32_16x16x32_bf16 v[80:83], v[178:181], v[206:209], v[80:83]
	v_mfma_f32_16x16x32_bf16 v[68:71], v[170:173], v[214:217], v[68:71]
	v_mfma_f32_16x16x32_bf16 v[64:67], v[178:181], v[214:217], v[64:67]
	v_mfma_f32_16x16x32_bf16 v[116:119], v[174:177], v[190:193], v[116:119]
	v_mfma_f32_16x16x32_bf16 v[112:115], v[182:185], v[190:193], v[112:115]
	v_mfma_f32_16x16x32_bf16 v[100:103], v[174:177], v[202:205], v[100:103]
	v_mfma_f32_16x16x32_bf16 v[96:99], v[182:185], v[202:205], v[96:99]
	v_mfma_f32_16x16x32_bf16 v[84:87], v[174:177], v[210:213], v[84:87]
	v_mfma_f32_16x16x32_bf16 v[80:83], v[182:185], v[210:213], v[80:83]
	v_mfma_f32_16x16x32_bf16 v[68:71], v[174:177], v[218:221], v[68:71]
	v_mfma_f32_16x16x32_bf16 v[64:67], v[182:185], v[218:221], v[64:67]
	s_setprio 0
	s_barrier
	s_add_i32 s64, s78, s2
	v_lshl_add_u64 v[160:161], v[160:161], 0, s[18:19]
	s_mov_b32 m0, s64
	ds_read_b128 v[186:189], v167 offset:49152
	ds_read_b128 v[190:193], v167 offset:50176
	ds_read_b128 v[198:201], v167 offset:51200
	ds_read_b128 v[202:205], v167 offset:52224
	ds_read_b128 v[206:209], v167 offset:53248
	ds_read_b128 v[210:213], v167 offset:54272
	ds_read_b128 v[214:217], v167 offset:55296
	ds_read_b128 v[218:221], v167 offset:56320
	global_load_lds_dwordx4 v[160:161], off
	s_add_i32 m0, s64, 0x2000
	s_add_u32 s62, s62, 0x40080
	v_lshl_add_u64 v[160:161], v[194:195], 0, s[18:19]
	s_addc_u32 s63, s63, 0
	s_add_i32 s64, s79, s2
	global_load_lds_dwordx4 v[160:161], off
	v_lshl_add_u64 v[160:161], s[62:63], 0, v[130:131]
	s_mov_b32 m0, s64
	s_nop 0
	global_load_lds_dwordx4 v[160:161], off
	v_lshl_add_u64 v[160:161], s[62:63], 0, v[134:135]
	s_add_i32 m0, s64, 0x2000
	s_nop 0
	global_load_lds_dwordx4 v[160:161], off
	v_lshl_add_u64 v[160:161], v[222:223], 0, s[18:19]
	s_mov_b32 m0, s66
	s_nop 0
	global_load_lds_dwordx4 v[160:161], off
	v_lshl_add_u64 v[160:161], v[224:225], 0, s[18:19]
	s_mov_b32 m0, s67
	s_nop 0
	global_load_lds_dwordx4 v[160:161], off
	s_waitcnt vmcnt(8)
	s_waitcnt lgkmcnt(0)
	s_barrier
	s_setprio 1
	s_waitcnt lgkmcnt(0)
	v_mfma_f32_16x16x32_bf16 v[60:63], v[144:147], v[186:189], v[60:63]
	v_mfma_f32_16x16x32_bf16 v[56:59], v[152:155], v[186:189], v[56:59]
	v_mfma_f32_16x16x32_bf16 v[44:47], v[144:147], v[198:201], v[44:47]
	v_mfma_f32_16x16x32_bf16 v[40:43], v[152:155], v[198:201], v[40:43]
	v_mfma_f32_16x16x32_bf16 v[28:31], v[144:147], v[206:209], v[28:31]
	v_mfma_f32_16x16x32_bf16 v[24:27], v[152:155], v[206:209], v[24:27]
	v_mfma_f32_16x16x32_bf16 v[12:15], v[144:147], v[214:217], v[12:15]
	v_mfma_f32_16x16x32_bf16 v[8:11], v[152:155], v[214:217], v[8:11]
	v_mfma_f32_16x16x32_bf16 v[60:63], v[148:151], v[190:193], v[60:63]
	v_mfma_f32_16x16x32_bf16 v[56:59], v[156:159], v[190:193], v[56:59]
	v_mfma_f32_16x16x32_bf16 v[44:47], v[148:151], v[202:205], v[44:47]
	v_mfma_f32_16x16x32_bf16 v[40:43], v[156:159], v[202:205], v[40:43]
	v_mfma_f32_16x16x32_bf16 v[28:31], v[148:151], v[210:213], v[28:31]
	v_mfma_f32_16x16x32_bf16 v[24:27], v[156:159], v[210:213], v[24:27]
	v_mfma_f32_16x16x32_bf16 v[12:15], v[148:151], v[218:221], v[12:15]
	v_mfma_f32_16x16x32_bf16 v[8:11], v[156:159], v[218:221], v[8:11]
	s_setprio 0
	s_setprio 1
	v_mfma_f32_16x16x32_bf16 v[52:55], v[170:173], v[186:189], v[52:55]
	v_mfma_f32_16x16x32_bf16 v[48:51], v[178:181], v[186:189], v[48:51]
	v_mfma_f32_16x16x32_bf16 v[36:39], v[170:173], v[198:201], v[36:39]
	v_mfma_f32_16x16x32_bf16 v[32:35], v[178:181], v[198:201], v[32:35]
	v_mfma_f32_16x16x32_bf16 v[20:23], v[170:173], v[206:209], v[20:23]
	v_mfma_f32_16x16x32_bf16 v[16:19], v[178:181], v[206:209], v[16:19]
	v_mfma_f32_16x16x32_bf16 v[4:7], v[170:173], v[214:217], v[4:7]
	v_mfma_f32_16x16x32_bf16 v[0:3], v[178:181], v[214:217], v[0:3]
	v_mfma_f32_16x16x32_bf16 v[52:55], v[174:177], v[190:193], v[52:55]
	v_mfma_f32_16x16x32_bf16 v[48:51], v[182:185], v[190:193], v[48:51]
	v_mfma_f32_16x16x32_bf16 v[36:39], v[174:177], v[202:205], v[36:39]
	v_mfma_f32_16x16x32_bf16 v[32:35], v[182:185], v[202:205], v[32:35]
	v_mfma_f32_16x16x32_bf16 v[20:23], v[174:177], v[210:213], v[20:23]
	v_mfma_f32_16x16x32_bf16 v[16:19], v[182:185], v[210:213], v[16:19]
	v_mfma_f32_16x16x32_bf16 v[4:7], v[174:177], v[218:221], v[4:7]
	v_mfma_f32_16x16x32_bf16 v[0:3], v[182:185], v[218:221], v[0:3]
	s_setprio 0
	s_barrier
	s_add_i32 s77, s77, 2
	s_add_u32 s60, s60, 0x100
	s_addc_u32 s61, s61, 0
	s_add_u32 s75, s75, 0x100
	s_addc_u32 s76, s76, 0

.LBB0_1121:
	s_ashr_i32 s23, s22, 31
	s_lshl_b64 s[12:13], s[22:23], 19
	s_add_u32 s24, s34, s12
	s_addc_u32 s25, s35, s13
	s_and_b64 s[12:13], s[0:1], exec
	s_cselect_b32 s12, s25, s37
	s_cselect_b32 s13, s24, s36
	s_ashr_i32 s21, s20, 31
	s_lshl_b64 s[26:27], s[20:21], 19
	s_add_u32 s26, s42, s26
	s_addc_u32 s27, s43, s27
	s_and_b64 s[44:45], s[0:1], exec
	s_cselect_b32 s21, s27, s41
	s_cselect_b32 s23, s26, s40
	s_add_u32 s36, s36, 0x40080
	s_addc_u32 s37, s37, 0
	s_add_u32 s61, s40, 0x100
	s_addc_u32 s62, s41, 0
	s_mov_b32 s63, -2
	ds_read_b128 v[156:159], v151
	ds_read_b128 v[160:163], v151 offset:1024
	ds_read_b128 v[164:167], v151 offset:2048
	ds_read_b128 v[168:171], v151 offset:3072
	ds_read_b128 v[172:175], v152
	ds_read_b128 v[176:179], v152 offset:1024
	ds_read_b128 v[180:183], v152 offset:2048
	ds_read_b128 v[184:187], v152 offset:3072
	s_add_u32 s40, s36, 0xfffc0080
	s_addc_u32 s41, s37, -1
	s_cmp_eq_u32 s63, 12
	s_cselect_b32 s45, s12, s41
	s_cselect_b32 s44, s13, s40
	s_cselect_b32 s41, s21, s62
	s_cselect_b32 s40, s23, s61
	v_lshl_add_u64 v[148:149], s[36:37], 0, v[140:141]
	s_add_i32 m0, s15, 0xc000
	ds_read_b128 v[188:191], v153
	ds_read_b128 v[192:195], v153 offset:1024
	ds_read_b128 v[198:201], v153 offset:2048
	ds_read_b128 v[202:205], v153 offset:3072
	ds_read_b128 v[206:209], v153 offset:4096
	ds_read_b128 v[210:213], v153 offset:5120
	ds_read_b128 v[214:217], v153 offset:6144
	ds_read_b128 v[218:221], v153 offset:7168
	global_load_lds_dwordx4 v[148:149], off
	v_lshl_add_u64 v[148:149], s[36:37], 0, v[142:143]
	s_add_i32 m0, s15, 0xe000
	s_nop 0
	global_load_lds_dwordx4 v[148:149], off
	s_waitcnt vmcnt(8)
	s_waitcnt lgkmcnt(0)
	s_barrier
	s_setprio 1
	s_waitcnt lgkmcnt(0)
	v_mfma_f32_16x16x32_bf16 v[124:127], v[156:159], v[188:191], 0
	v_mfma_f32_16x16x32_bf16 v[120:123], v[164:167], v[188:191], 0
	v_mfma_f32_16x16x32_bf16 v[108:111], v[156:159], v[198:201], 0
	v_mfma_f32_16x16x32_bf16 v[104:107], v[164:167], v[198:201], 0
	v_mfma_f32_16x16x32_bf16 v[92:95], v[156:159], v[206:209], 0
	v_mfma_f32_16x16x32_bf16 v[88:91], v[164:167], v[206:209], 0
	v_mfma_f32_16x16x32_bf16 v[76:79], v[156:159], v[214:217], 0
	v_mfma_f32_16x16x32_bf16 v[72:75], v[164:167], v[214:217], 0
	v_mfma_f32_16x16x32_bf16 v[124:127], v[160:163], v[192:195], v[124:127]
	v_mfma_f32_16x16x32_bf16 v[120:123], v[168:171], v[192:195], v[120:123]
	v_mfma_f32_16x16x32_bf16 v[108:111], v[160:163], v[202:205], v[108:111]
	v_mfma_f32_16x16x32_bf16 v[104:107], v[168:171], v[202:205], v[104:107]
	v_mfma_f32_16x16x32_bf16 v[92:95], v[160:163], v[210:213], v[92:95]
	v_mfma_f32_16x16x32_bf16 v[88:91], v[168:171], v[210:213], v[88:91]
	v_mfma_f32_16x16x32_bf16 v[76:79], v[160:163], v[218:221], v[76:79]
	v_mfma_f32_16x16x32_bf16 v[72:75], v[168:171], v[218:221], v[72:75]
	s_setprio 0
	s_setprio 1
	v_mfma_f32_16x16x32_bf16 v[116:119], v[172:175], v[188:191], 0
	v_mfma_f32_16x16x32_bf16 v[112:115], v[180:183], v[188:191], 0
	v_mfma_f32_16x16x32_bf16 v[100:103], v[172:175], v[198:201], 0
	v_mfma_f32_16x16x32_bf16 v[96:99], v[180:183], v[198:201], 0
	v_mfma_f32_16x16x32_bf16 v[84:87], v[172:175], v[206:209], 0
	v_mfma_f32_16x16x32_bf16 v[80:83], v[180:183], v[206:209], 0
	v_mfma_f32_16x16x32_bf16 v[68:71], v[172:175], v[214:217], 0
	v_mfma_f32_16x16x32_bf16 v[64:67], v[180:183], v[214:217], 0
	v_mfma_f32_16x16x32_bf16 v[116:119], v[176:179], v[192:195], v[116:119]
	v_mfma_f32_16x16x32_bf16 v[112:115], v[184:187], v[192:195], v[112:115]
	v_mfma_f32_16x16x32_bf16 v[100:103], v[176:179], v[202:205], v[100:103]
	v_mfma_f32_16x16x32_bf16 v[96:99], v[184:187], v[202:205], v[96:99]
	v_mfma_f32_16x16x32_bf16 v[84:87], v[176:179], v[210:213], v[84:87]
	v_mfma_f32_16x16x32_bf16 v[80:83], v[184:187], v[210:213], v[80:83]
	v_mfma_f32_16x16x32_bf16 v[68:71], v[176:179], v[218:221], v[68:71]
	v_mfma_f32_16x16x32_bf16 v[64:67], v[184:187], v[218:221], v[64:67]
	s_setprio 0
	s_barrier
	s_add_i32 s64, s57, s2
	v_lshl_add_u64 v[148:149], s[40:41], 0, v[132:133]
	s_mov_b32 m0, s64
	ds_read_b128 v[188:191], v153 offset:16384
	ds_read_b128 v[192:195], v153 offset:17408
	ds_read_b128 v[198:201], v153 offset:18432
	ds_read_b128 v[202:205], v153 offset:19456
	ds_read_b128 v[206:209], v153 offset:20480
	ds_read_b128 v[210:213], v153 offset:21504
	ds_read_b128 v[214:217], v153 offset:22528
	ds_read_b128 v[218:221], v153 offset:23552
	global_load_lds_dwordx4 v[148:149], off
	s_add_i32 m0, s64, 0x2000
	s_add_u32 s64, s40, 0x40000
	v_lshl_add_u64 v[222:223], s[40:41], 0, v[128:129]
	s_addc_u32 s65, s41, 0
	s_add_i32 s66, s58, s2
	global_load_lds_dwordx4 v[222:223], off
	v_lshl_add_u64 v[224:225], s[64:65], 0, v[132:133]
	s_mov_b32 m0, s66
	v_lshl_add_u64 v[226:227], s[44:45], 0, v[130:131]
	global_load_lds_dwordx4 v[224:225], off
	v_lshl_add_u64 v[224:225], s[64:65], 0, v[128:129]
	s_add_i32 m0, s66, 0x2000
	s_nop 0
	global_load_lds_dwordx4 v[224:225], off
	v_lshl_add_u64 v[224:225], s[44:45], 0, v[134:135]
	s_mov_b32 m0, s15
	s_nop 0
	global_load_lds_dwordx4 v[224:225], off
	s_mov_b32 m0, s46
	s_nop 0
	global_load_lds_dwordx4 v[226:227], off
	s_waitcnt vmcnt(8)
	s_waitcnt lgkmcnt(0)
	s_barrier
	s_setprio 1
	s_waitcnt lgkmcnt(0)
	v_mfma_f32_16x16x32_bf16 v[60:63], v[156:159], v[188:191], 0
	v_mfma_f32_16x16x32_bf16 v[56:59], v[164:167], v[188:191], 0
	v_mfma_f32_16x16x32_bf16 v[44:47], v[156:159], v[198:201], 0
	v_mfma_f32_16x16x32_bf16 v[40:43], v[164:167], v[198:201], 0
	v_mfma_f32_16x16x32_bf16 v[28:31], v[156:159], v[206:209], 0
	v_mfma_f32_16x16x32_bf16 v[24:27], v[164:167], v[206:209], 0
	v_mfma_f32_16x16x32_bf16 v[12:15], v[156:159], v[214:217], 0
	v_mfma_f32_16x16x32_bf16 v[8:11], v[164:167], v[214:217], 0
	v_mfma_f32_16x16x32_bf16 v[60:63], v[160:163], v[192:195], v[60:63]
	v_mfma_f32_16x16x32_bf16 v[56:59], v[168:171], v[192:195], v[56:59]
	v_mfma_f32_16x16x32_bf16 v[44:47], v[160:163], v[202:205], v[44:47]
	v_mfma_f32_16x16x32_bf16 v[40:43], v[168:171], v[202:205], v[40:43]
	v_mfma_f32_16x16x32_bf16 v[28:31], v[160:163], v[210:213], v[28:31]
	v_mfma_f32_16x16x32_bf16 v[24:27], v[168:171], v[210:213], v[24:27]
	v_mfma_f32_16x16x32_bf16 v[12:15], v[160:163], v[218:221], v[12:15]
	v_mfma_f32_16x16x32_bf16 v[8:11], v[168:171], v[218:221], v[8:11]
	s_setprio 0
	s_setprio 1
	v_mfma_f32_16x16x32_bf16 v[52:55], v[172:175], v[188:191], 0
	v_mfma_f32_16x16x32_bf16 v[48:51], v[180:183], v[188:191], 0
	v_mfma_f32_16x16x32_bf16 v[36:39], v[172:175], v[198:201], 0
	v_mfma_f32_16x16x32_bf16 v[32:35], v[180:183], v[198:201], 0
	v_mfma_f32_16x16x32_bf16 v[20:23], v[172:175], v[206:209], 0
	v_mfma_f32_16x16x32_bf16 v[16:19], v[180:183], v[206:209], 0
	v_mfma_f32_16x16x32_bf16 v[4:7], v[172:175], v[214:217], 0
	v_mfma_f32_16x16x32_bf16 v[0:3], v[180:183], v[214:217], 0
	v_mfma_f32_16x16x32_bf16 v[52:55], v[176:179], v[192:195], v[52:55]
	v_mfma_f32_16x16x32_bf16 v[48:51], v[184:187], v[192:195], v[48:51]
	v_mfma_f32_16x16x32_bf16 v[36:39], v[176:179], v[202:205], v[36:39]
	v_mfma_f32_16x16x32_bf16 v[32:35], v[184:187], v[202:205], v[32:35]
	v_mfma_f32_16x16x32_bf16 v[20:23], v[176:179], v[210:213], v[20:23]
	v_mfma_f32_16x16x32_bf16 v[16:19], v[184:187], v[210:213], v[16:19]
	v_mfma_f32_16x16x32_bf16 v[4:7], v[176:179], v[218:221], v[4:7]
	v_mfma_f32_16x16x32_bf16 v[0:3], v[184:187], v[218:221], v[0:3]
	s_setprio 0
	s_barrier
	s_add_i32 s64, 0, 0x18000
	v_add_u32_e32 v136, s64, v150
	s_add_i32 s65, 0, 0x1c000
	ds_read_b128 v[156:159], v136
	ds_read_b128 v[160:163], v136 offset:1024
	ds_read_b128 v[164:167], v136 offset:2048
	ds_read_b128 v[168:171], v136 offset:3072
	v_add_u32_e32 v136, s65, v150
	ds_read_b128 v[172:175], v136
	ds_read_b128 v[176:179], v136 offset:1024
	ds_read_b128 v[180:183], v136 offset:2048
	ds_read_b128 v[184:187], v136 offset:3072
	s_add_u32 s44, s44, 0x40000
	s_addc_u32 s45, s45, 0
	s_mov_b32 m0, s47
	v_lshl_add_u64 v[228:229], s[44:45], 0, v[134:135]
	ds_read_b128 v[188:191], v153 offset:32768
	ds_read_b128 v[192:195], v153 offset:33792
	ds_read_b128 v[198:201], v153 offset:34816
	ds_read_b128 v[202:205], v153 offset:35840
	ds_read_b128 v[206:209], v153 offset:36864
	ds_read_b128 v[210:213], v153 offset:37888
	ds_read_b128 v[214:217], v153 offset:38912
	ds_read_b128 v[218:221], v153 offset:39936
	global_load_lds_dwordx4 v[228:229], off
	v_lshl_add_u64 v[228:229], s[44:45], 0, v[130:131]
	s_mov_b32 m0, s48
	s_nop 0
	global_load_lds_dwordx4 v[228:229], off
	s_waitcnt vmcnt(8)
	s_waitcnt lgkmcnt(0)
	s_barrier
	s_setprio 1
	s_waitcnt lgkmcnt(0)
	v_mfma_f32_16x16x32_bf16 v[124:127], v[156:159], v[188:191], v[124:127]
	v_mfma_f32_16x16x32_bf16 v[120:123], v[164:167], v[188:191], v[120:123]
	v_mfma_f32_16x16x32_bf16 v[108:111], v[156:159], v[198:201], v[108:111]
	v_mfma_f32_16x16x32_bf16 v[104:107], v[164:167], v[198:201], v[104:107]
	v_mfma_f32_16x16x32_bf16 v[92:95], v[156:159], v[206:209], v[92:95]
	v_mfma_f32_16x16x32_bf16 v[88:91], v[164:167], v[206:209], v[88:91]
	v_mfma_f32_16x16x32_bf16 v[76:79], v[156:159], v[214:217], v[76:79]
	v_mfma_f32_16x16x32_bf16 v[72:75], v[164:167], v[214:217], v[72:75]
	v_mfma_f32_16x16x32_bf16 v[124:127], v[160:163], v[192:195], v[124:127]
	v_mfma_f32_16x16x32_bf16 v[120:123], v[168:171], v[192:195], v[120:123]
	v_mfma_f32_16x16x32_bf16 v[108:111], v[160:163], v[202:205], v[108:111]
	v_mfma_f32_16x16x32_bf16 v[104:107], v[168:171], v[202:205], v[104:107]
	v_mfma_f32_16x16x32_bf16 v[92:95], v[160:163], v[210:213], v[92:95]
	v_mfma_f32_16x16x32_bf16 v[88:91], v[168:171], v[210:213], v[88:91]
	v_mfma_f32_16x16x32_bf16 v[76:79], v[160:163], v[218:221], v[76:79]
	v_mfma_f32_16x16x32_bf16 v[72:75], v[168:171], v[218:221], v[72:75]
	s_setprio 0
	s_setprio 1
	v_mfma_f32_16x16x32_bf16 v[116:119], v[172:175], v[188:191], v[116:119]
	v_mfma_f32_16x16x32_bf16 v[112:115], v[180:183], v[188:191], v[112:115]
	v_mfma_f32_16x16x32_bf16 v[100:103], v[172:175], v[198:201], v[100:103]
	v_mfma_f32_16x16x32_bf16 v[96:99], v[180:183], v[198:201], v[96:99]
	v_mfma_f32_16x16x32_bf16 v[84:87], v[172:175], v[206:209], v[84:87]
	v_mfma_f32_16x16x32_bf16 v[80:83], v[180:183], v[206:209], v[80:83]
	v_mfma_f32_16x16x32_bf16 v[68:71], v[172:175], v[214:217], v[68:71]
	v_mfma_f32_16x16x32_bf16 v[64:67], v[180:183], v[214:217], v[64:67]
	v_mfma_f32_16x16x32_bf16 v[116:119], v[176:179], v[192:195], v[116:119]
	v_mfma_f32_16x16x32_bf16 v[112:115], v[184:187], v[192:195], v[112:115]
	v_mfma_f32_16x16x32_bf16 v[100:103], v[176:179], v[202:205], v[100:103]
	v_mfma_f32_16x16x32_bf16 v[96:99], v[184:187], v[202:205], v[96:99]
	v_mfma_f32_16x16x32_bf16 v[84:87], v[176:179], v[210:213], v[84:87]
	v_mfma_f32_16x16x32_bf16 v[80:83], v[184:187], v[210:213], v[80:83]
	v_mfma_f32_16x16x32_bf16 v[68:71], v[176:179], v[218:221], v[68:71]
	v_mfma_f32_16x16x32_bf16 v[64:67], v[184:187], v[218:221], v[64:67]
	s_setprio 0
	s_barrier
	s_add_i32 s44, s64, s2
	v_lshl_add_u64 v[148:149], v[148:149], 0, s[16:17]
	s_mov_b32 m0, s44
	ds_read_b128 v[188:191], v153 offset:49152
	ds_read_b128 v[192:195], v153 offset:50176
	ds_read_b128 v[198:201], v153 offset:51200
	ds_read_b128 v[202:205], v153 offset:52224
	ds_read_b128 v[206:209], v153 offset:53248
	ds_read_b128 v[210:213], v153 offset:54272
	ds_read_b128 v[214:217], v153 offset:55296
	ds_read_b128 v[218:221], v153 offset:56320
	global_load_lds_dwordx4 v[148:149], off
	s_add_i32 m0, s44, 0x2000
	s_add_u32 s40, s40, 0x40080
	v_lshl_add_u64 v[148:149], v[222:223], 0, s[16:17]
	s_addc_u32 s41, s41, 0
	s_add_i32 s44, s65, s2
	global_load_lds_dwordx4 v[148:149], off
	v_lshl_add_u64 v[148:149], s[40:41], 0, v[132:133]
	s_mov_b32 m0, s44
	s_nop 0
	global_load_lds_dwordx4 v[148:149], off
	v_lshl_add_u64 v[148:149], s[40:41], 0, v[128:129]
	s_add_i32 m0, s44, 0x2000
	s_nop 0
	global_load_lds_dwordx4 v[148:149], off
	v_lshl_add_u64 v[148:149], v[224:225], 0, s[16:17]
	s_mov_b32 m0, s54
	s_nop 0
	global_load_lds_dwordx4 v[148:149], off
	v_lshl_add_u64 v[148:149], v[226:227], 0, s[16:17]
	s_mov_b32 m0, s55
	s_nop 0
	global_load_lds_dwordx4 v[148:149], off
	s_waitcnt vmcnt(8)
	s_waitcnt lgkmcnt(0)
	s_barrier
	s_setprio 1
	s_waitcnt lgkmcnt(0)
	v_mfma_f32_16x16x32_bf16 v[60:63], v[156:159], v[188:191], v[60:63]
	v_mfma_f32_16x16x32_bf16 v[56:59], v[164:167], v[188:191], v[56:59]
	v_mfma_f32_16x16x32_bf16 v[44:47], v[156:159], v[198:201], v[44:47]
	v_mfma_f32_16x16x32_bf16 v[40:43], v[164:167], v[198:201], v[40:43]
	v_mfma_f32_16x16x32_bf16 v[28:31], v[156:159], v[206:209], v[28:31]
	v_mfma_f32_16x16x32_bf16 v[24:27], v[164:167], v[206:209], v[24:27]
	v_mfma_f32_16x16x32_bf16 v[12:15], v[156:159], v[214:217], v[12:15]
	v_mfma_f32_16x16x32_bf16 v[8:11], v[164:167], v[214:217], v[8:11]
	v_mfma_f32_16x16x32_bf16 v[60:63], v[160:163], v[192:195], v[60:63]
	v_mfma_f32_16x16x32_bf16 v[56:59], v[168:171], v[192:195], v[56:59]
	v_mfma_f32_16x16x32_bf16 v[44:47], v[160:163], v[202:205], v[44:47]
	v_mfma_f32_16x16x32_bf16 v[40:43], v[168:171], v[202:205], v[40:43]
	v_mfma_f32_16x16x32_bf16 v[28:31], v[160:163], v[210:213], v[28:31]
	v_mfma_f32_16x16x32_bf16 v[24:27], v[168:171], v[210:213], v[24:27]
	v_mfma_f32_16x16x32_bf16 v[12:15], v[160:163], v[218:221], v[12:15]
	v_mfma_f32_16x16x32_bf16 v[8:11], v[168:171], v[218:221], v[8:11]
	s_setprio 0
	s_setprio 1
	v_mfma_f32_16x16x32_bf16 v[52:55], v[172:175], v[188:191], v[52:55]
	v_mfma_f32_16x16x32_bf16 v[48:51], v[180:183], v[188:191], v[48:51]
	v_mfma_f32_16x16x32_bf16 v[36:39], v[172:175], v[198:201], v[36:39]
	v_mfma_f32_16x16x32_bf16 v[32:35], v[180:183], v[198:201], v[32:35]
	v_mfma_f32_16x16x32_bf16 v[20:23], v[172:175], v[206:209], v[20:23]
	v_mfma_f32_16x16x32_bf16 v[16:19], v[180:183], v[206:209], v[16:19]
	v_mfma_f32_16x16x32_bf16 v[4:7], v[172:175], v[214:217], v[4:7]
	v_mfma_f32_16x16x32_bf16 v[0:3], v[180:183], v[214:217], v[0:3]
	v_mfma_f32_16x16x32_bf16 v[52:55], v[176:179], v[192:195], v[52:55]
	v_mfma_f32_16x16x32_bf16 v[48:51], v[184:187], v[192:195], v[48:51]
	v_mfma_f32_16x16x32_bf16 v[36:39], v[176:179], v[202:205], v[36:39]
	v_mfma_f32_16x16x32_bf16 v[32:35], v[184:187], v[202:205], v[32:35]
	v_mfma_f32_16x16x32_bf16 v[20:23], v[176:179], v[210:213], v[20:23]
	v_mfma_f32_16x16x32_bf16 v[16:19], v[184:187], v[210:213], v[16:19]
	v_mfma_f32_16x16x32_bf16 v[4:7], v[176:179], v[218:221], v[4:7]
	v_mfma_f32_16x16x32_bf16 v[0:3], v[184:187], v[218:221], v[0:3]
	s_setprio 0
	s_barrier
	s_add_i32 s63, s63, 2
	s_add_u32 s36, s36, 0x100
	s_addc_u32 s37, s37, 0
	s_add_u32 s61, s61, 0x100
	s_addc_u32 s62, s62, 0
